# code placement: every 32-MFMA block of the four GEMM K-loops starts 8-byte aligned (.p2align 3 in the load-segment tail)
# baseline (speedup 1.0000x reference)
; #define PG8_STAGE(bufoff, gbase, voff) do { _Pragma("unroll") for (int _i = 0; _i < 2; ++_i) \
;         __builtin_amdgcn_global_load_lds((const unsigned*)((const char*)(gbase) + (voff)[_i]), (PG8_LAS unsigned*)(lds + (bufoff) + ldsw + _i * 8192), 16, 0, 0); } while (0)
; #define PG8_LDA(dst, b, h) do { _Pragma("unroll") for (int m = 0; m < 4; ++m) _Pragma("unroll") for (int k = 0; k < 2; ++k) dst[m][k] = *(const PG8_LAS bf16x8*)(lds + PG8_SA(b, h) + aoff + m * 2048 + k * 1024); } while (0)
; #define PG8_LDB(dst, b, h) do { _Pragma("unroll") for (int n = 0; n < 2; ++n) _Pragma("unroll") for (int k = 0; k < 2; ++k) dst[n][k] = *(const PG8_LAS bf16x8*)(lds + PG8_SB(b, h) + boff + n * 2048 + k * 1024); } while (0)
; #define PG8_MMA(ai, bj, At, Bt) do { __builtin_amdgcn_s_setprio(1); _Pragma("unroll") for (int m = 0; m < 4; ++m) _Pragma("unroll") for (int n = 0; n < 2; ++n) _Pragma("unroll") for (int k = 0; k < 2; ++k) \
;         acc[ai][bj][m][n] = __builtin_amdgcn_mfma_f32_16x16x32_bf16(Bt[n][k], At[m][k], acc[ai][bj][m][n], 0, 0, 0); __builtin_amdgcn_s_setprio(0); } while (0)
; template <class Epi, class Sched, bool ALIGN_EPI = false, bool SP2 = false>
; __device__ __forceinline__ void gemm_phase(PG8_LAS unsigned char* lds, const Gemm g, const Sched& S, const Epi& E, int tid_in) {
;     ...
;             if constexpr (SP2) {
;             PG8_LDB(B0, 0, 0); PG8_LDB(B1, 0, 1); PG8_SCHED; PG8_LDA(At, 0, 0); PG8_STAGE(PG8_SA(1, 1), a1 + hstep, voffA);
;             PG8_WAIT_V(8); PG8_WAIT_L(0); PG8_BAR; PG8_MMA(0, 0, At, B0); PG8_MMA(0, 1, At, B1); PG8_BAR; PG8_SCHED;
;             PG8_LDA(At, 0, 1); PG8_STAGE(PG8_SB(0, 0), b2, voffB); PG8_STAGE(PG8_SB(0, 1), b2 + hstep, voffB); PG8_STAGE(PG8_SA(0, 0), a2, voffA);
;             PG8_WAIT_V(8); PG8_WAIT_L(0); PG8_BAR; PG8_MMA(1, 0, At, B0); PG8_MMA(1, 1, At, B1); PG8_BAR; PG8_SCHED;
;             PG8_LDB(B0, 1, 0); PG8_LDB(B1, 1, 1); PG8_SCHED; PG8_LDA(At, 1, 0); PG8_STAGE(PG8_SA(0, 1), a2 + hstep, voffA);
;             PG8_WAIT_V(8); PG8_WAIT_L(0); PG8_BAR; PG8_MMA(0, 0, At, B0); PG8_MMA(0, 1, At, B1); PG8_BAR; PG8_SCHED;
;             PG8_LDA(At, 1, 1); PG8_STAGE(PG8_SB(1, 0), b3, voffB); PG8_STAGE(PG8_SB(1, 1), b3 + hstep, voffB); PG8_STAGE(PG8_SA(1, 0), a3, voffA);
;             PG8_WAIT_V(8); PG8_WAIT_L(0); PG8_BAR; PG8_MMA(1, 0, At, B0); PG8_MMA(1, 1, At, B1); PG8_BAR; PG8_SCHED;
.LBB0_59:
	s_add_u32 s28, s6, 0xfff80080
	s_addc_u32 s29, s7, -1
	s_add_i32 s60, 0, 0x10000
	s_cmp_eq_u32 s59, 28
	s_cselect_b32 s31, s23, s29
	s_cselect_b32 s30, s45, s28
	v_add_u32_e32 v32, s60, v149
	s_cselect_b32 s29, s21, s47
	s_cselect_b32 s28, s57, s58
	s_add_i32 s62, 0, 0x14000
	ds_read_b128 v[142:145], v32
	ds_read_b128 v[152:155], v32 offset:1024
	ds_read_b128 v[156:159], v32 offset:2048
	ds_read_b128 v[160:163], v32 offset:3072
	v_add_u32_e32 v32, s62, v149
	ds_read_b128 v[164:167], v32
	ds_read_b128 v[186:189], v32 offset:1024
	ds_read_b128 v[190:193], v32 offset:2048
	ds_read_b128 v[194:197], v32 offset:3072
	v_lshl_add_u64 v[146:147], s[6:7], 0, v[138:139]
	s_add_i32 m0, s42, 0xc000
	ds_read_b128 v[212:215], v151
	ds_read_b128 v[220:223], v151 offset:1024
	ds_read_b128 v[224:227], v151 offset:2048
	ds_read_b128 v[228:231], v151 offset:3072
	ds_read_b128 v[232:235], v151 offset:4096
	ds_read_b128 v[236:239], v151 offset:5120
	ds_read_b128 v[240:243], v151 offset:6144
	ds_read_b128 v[244:247], v151 offset:7168
	global_load_lds_dwordx4 v[146:147], off
	v_lshl_add_u64 v[146:147], s[6:7], 0, v[140:141]
	s_add_i32 m0, s42, 0xe000
	s_nop 0
	global_load_lds_dwordx4 v[146:147], off
	s_waitcnt vmcnt(8)
	s_waitcnt lgkmcnt(0)
	.p2align	3
	s_setprio 1
	s_barrier
	v_mfma_f32_16x16x32_bf16 v[126:129], v[142:145], v[212:215], v[126:129]
	v_mfma_f32_16x16x32_bf16 v[122:125], v[156:159], v[212:215], v[122:125]
	v_mfma_f32_16x16x32_bf16 v[110:113], v[142:145], v[224:227], v[110:113]
	v_mfma_f32_16x16x32_bf16 v[106:109], v[156:159], v[224:227], v[106:109]
	v_mfma_f32_16x16x32_bf16 v[94:97], v[142:145], v[232:235], v[94:97]
	v_mfma_f32_16x16x32_bf16 v[90:93], v[156:159], v[232:235], v[90:93]
	v_mfma_f32_16x16x32_bf16 v[78:81], v[142:145], v[240:243], v[78:81]
	v_mfma_f32_16x16x32_bf16 v[74:77], v[156:159], v[240:243], v[74:77]
	v_mfma_f32_16x16x32_bf16 v[126:129], v[152:155], v[220:223], v[126:129]
	v_mfma_f32_16x16x32_bf16 v[122:125], v[160:163], v[220:223], v[122:125]
	v_mfma_f32_16x16x32_bf16 v[110:113], v[152:155], v[228:231], v[110:113]
	v_mfma_f32_16x16x32_bf16 v[106:109], v[160:163], v[228:231], v[106:109]
	v_mfma_f32_16x16x32_bf16 v[94:97], v[152:155], v[236:239], v[94:97]
	v_mfma_f32_16x16x32_bf16 v[90:93], v[160:163], v[236:239], v[90:93]
	v_mfma_f32_16x16x32_bf16 v[78:81], v[152:155], v[244:247], v[78:81]
	v_mfma_f32_16x16x32_bf16 v[74:77], v[160:163], v[244:247], v[74:77]
	v_mfma_f32_16x16x32_bf16 v[118:121], v[164:167], v[212:215], v[118:121]
	v_mfma_f32_16x16x32_bf16 v[114:117], v[190:193], v[212:215], v[114:117]
	v_mfma_f32_16x16x32_bf16 v[102:105], v[164:167], v[224:227], v[102:105]
	v_mfma_f32_16x16x32_bf16 v[98:101], v[190:193], v[224:227], v[98:101]
	v_mfma_f32_16x16x32_bf16 v[86:89], v[164:167], v[232:235], v[86:89]
	v_mfma_f32_16x16x32_bf16 v[82:85], v[190:193], v[232:235], v[82:85]
	v_mfma_f32_16x16x32_bf16 v[70:73], v[164:167], v[240:243], v[70:73]
	v_mfma_f32_16x16x32_bf16 v[66:69], v[190:193], v[240:243], v[66:69]
	v_mfma_f32_16x16x32_bf16 v[118:121], v[186:189], v[220:223], v[118:121]
	v_mfma_f32_16x16x32_bf16 v[114:117], v[194:197], v[220:223], v[114:117]
	v_mfma_f32_16x16x32_bf16 v[102:105], v[186:189], v[228:231], v[102:105]
	v_mfma_f32_16x16x32_bf16 v[98:101], v[194:197], v[228:231], v[98:101]
	v_mfma_f32_16x16x32_bf16 v[86:89], v[186:189], v[236:239], v[86:89]
	v_mfma_f32_16x16x32_bf16 v[82:85], v[194:197], v[236:239], v[82:85]
	v_mfma_f32_16x16x32_bf16 v[70:73], v[186:189], v[244:247], v[70:73]
	v_mfma_f32_16x16x32_bf16 v[66:69], v[194:197], v[244:247], v[66:69]
	s_setprio 0
	s_barrier
	s_add_i32 s60, s60, s39
	v_lshl_add_u64 v[146:147], s[28:29], 0, v[134:135]
	s_mov_b32 m0, s60
	ds_read_b128 v[212:215], v151 offset:16384
	ds_read_b128 v[220:223], v151 offset:17408
	ds_read_b128 v[224:227], v151 offset:18432
	ds_read_b128 v[228:231], v151 offset:19456
	ds_read_b128 v[232:235], v151 offset:20480
	ds_read_b128 v[236:239], v151 offset:21504
	ds_read_b128 v[240:243], v151 offset:22528
	ds_read_b128 v[244:247], v151 offset:23552
	global_load_lds_dwordx4 v[146:147], off
	s_add_i32 m0, s60, 0x2000
	s_add_u32 s60, s28, 0x80000
	v_lshl_add_u64 v[168:169], s[28:29], 0, v[130:131]
	s_addc_u32 s61, s29, 0
	s_add_i32 s62, s62, s39
	global_load_lds_dwordx4 v[168:169], off
	v_lshl_add_u64 v[216:217], s[60:61], 0, v[134:135]
	s_mov_b32 m0, s62
	v_lshl_add_u64 v[248:249], s[30:31], 0, v[132:133]
	global_load_lds_dwordx4 v[216:217], off
	v_lshl_add_u64 v[216:217], s[60:61], 0, v[130:131]
	s_add_i32 m0, s62, 0x2000
	s_nop 0
	global_load_lds_dwordx4 v[216:217], off
	v_lshl_add_u64 v[216:217], s[30:31], 0, v[136:137]
	s_mov_b32 m0, s42
	s_nop 0
	global_load_lds_dwordx4 v[216:217], off
	s_mov_b32 m0, s43
	s_nop 0
	global_load_lds_dwordx4 v[248:249], off
	s_waitcnt vmcnt(8)
	s_waitcnt lgkmcnt(0)
	.p2align	3
	s_setprio 1
	s_barrier
; #define PG8_STAGE(bufoff, gbase, voff) do { _Pragma("unroll") for (int _i = 0; _i < 2; ++_i) \
;         __builtin_amdgcn_global_load_lds((const unsigned*)((const char*)(gbase) + (voff)[_i]), (PG8_LAS unsigned*)(lds + (bufoff) + ldsw + _i * 8192), 16, 0, 0); } while (0)
; #define PG8_LDA(dst, b, h) do { _Pragma("unroll") for (int m = 0; m < 4; ++m) _Pragma("unroll") for (int k = 0; k < 2; ++k) dst[m][k] = *(const PG8_LAS bf16x8*)(lds + PG8_SA(b, h) + aoff + m * 2048 + k * 1024); } while (0)
; #define PG8_LDB(dst, b, h) do { _Pragma("unroll") for (int n = 0; n < 2; ++n) _Pragma("unroll") for (int k = 0; k < 2; ++k) dst[n][k] = *(const PG8_LAS bf16x8*)(lds + PG8_SB(b, h) + boff + n * 2048 + k * 1024); } while (0)
; #define PG8_MMA(ai, bj, At, Bt) do { __builtin_amdgcn_s_setprio(1); _Pragma("unroll") for (int m = 0; m < 4; ++m) _Pragma("unroll") for (int n = 0; n < 2; ++n) _Pragma("unroll") for (int k = 0; k < 2; ++k) \
;         acc[ai][bj][m][n] = __builtin_amdgcn_mfma_f32_16x16x32_bf16(Bt[n][k], At[m][k], acc[ai][bj][m][n], 0, 0, 0); __builtin_amdgcn_s_setprio(0); } while (0)
; template <class Epi, class Sched, bool ALIGN_EPI = false, bool SP2 = false>
; __device__ __forceinline__ void gemm_phase(PG8_LAS unsigned char* lds, const Gemm g, const Sched& S, const Epi& E, int tid_in) {
;     ...
;             if constexpr (SP2) {
;             PG8_LDB(B0, 0, 0); PG8_LDB(B1, 0, 1); PG8_SCHED; PG8_LDA(At, 0, 0); PG8_STAGE(PG8_SA(1, 1), a1 + hstep, voffA);
;             PG8_WAIT_V(8); PG8_WAIT_L(0); PG8_BAR; PG8_MMA(0, 0, At, B0); PG8_MMA(0, 1, At, B1); PG8_BAR; PG8_SCHED;
;             PG8_LDA(At, 0, 1); PG8_STAGE(PG8_SB(0, 0), b2, voffB); PG8_STAGE(PG8_SB(0, 1), b2 + hstep, voffB); PG8_STAGE(PG8_SA(0, 0), a2, voffA);
;             PG8_WAIT_V(8); PG8_WAIT_L(0); PG8_BAR; PG8_MMA(1, 0, At, B0); PG8_MMA(1, 1, At, B1); PG8_BAR; PG8_SCHED;
;             PG8_LDB(B0, 1, 0); PG8_LDB(B1, 1, 1); PG8_SCHED; PG8_LDA(At, 1, 0); PG8_STAGE(PG8_SA(0, 1), a2 + hstep, voffA);
;             PG8_WAIT_V(8); PG8_WAIT_L(0); PG8_BAR; PG8_MMA(0, 0, At, B0); PG8_MMA(0, 1, At, B1); PG8_BAR; PG8_SCHED;
;             PG8_LDA(At, 1, 1); PG8_STAGE(PG8_SB(1, 0), b3, voffB); PG8_STAGE(PG8_SB(1, 1), b3 + hstep, voffB); PG8_STAGE(PG8_SA(1, 0), a3, voffA);
;             PG8_WAIT_V(8); PG8_WAIT_L(0); PG8_BAR; PG8_MMA(1, 0, At, B0); PG8_MMA(1, 1, At, B1); PG8_BAR; PG8_SCHED;
	v_mfma_f32_16x16x32_bf16 v[62:65], v[142:145], v[212:215], v[62:65]
	v_mfma_f32_16x16x32_bf16 v[58:61], v[156:159], v[212:215], v[58:61]
	v_mfma_f32_16x16x32_bf16 v[46:49], v[142:145], v[224:227], v[46:49]
	v_mfma_f32_16x16x32_bf16 v[42:45], v[156:159], v[224:227], v[42:45]
	v_mfma_f32_16x16x32_bf16 v[28:31], v[142:145], v[232:235], v[28:31]
	v_mfma_f32_16x16x32_bf16 v[24:27], v[156:159], v[232:235], v[24:27]
	v_mfma_f32_16x16x32_bf16 v[12:15], v[142:145], v[240:243], v[12:15]
	v_mfma_f32_16x16x32_bf16 v[8:11], v[156:159], v[240:243], v[8:11]
	v_mfma_f32_16x16x32_bf16 v[62:65], v[152:155], v[220:223], v[62:65]
	v_mfma_f32_16x16x32_bf16 v[58:61], v[160:163], v[220:223], v[58:61]
	v_mfma_f32_16x16x32_bf16 v[46:49], v[152:155], v[228:231], v[46:49]
	v_mfma_f32_16x16x32_bf16 v[42:45], v[160:163], v[228:231], v[42:45]
	v_mfma_f32_16x16x32_bf16 v[28:31], v[152:155], v[236:239], v[28:31]
	v_mfma_f32_16x16x32_bf16 v[24:27], v[160:163], v[236:239], v[24:27]
	v_mfma_f32_16x16x32_bf16 v[12:15], v[152:155], v[244:247], v[12:15]
	v_mfma_f32_16x16x32_bf16 v[8:11], v[160:163], v[244:247], v[8:11]
	v_mfma_f32_16x16x32_bf16 v[54:57], v[164:167], v[212:215], v[54:57]
	v_mfma_f32_16x16x32_bf16 v[50:53], v[190:193], v[212:215], v[50:53]
	v_mfma_f32_16x16x32_bf16 v[38:41], v[164:167], v[224:227], v[38:41]
	v_mfma_f32_16x16x32_bf16 v[34:37], v[190:193], v[224:227], v[34:37]
	v_mfma_f32_16x16x32_bf16 v[20:23], v[164:167], v[232:235], v[20:23]
	v_mfma_f32_16x16x32_bf16 v[16:19], v[190:193], v[232:235], v[16:19]
	v_mfma_f32_16x16x32_bf16 v[4:7], v[164:167], v[240:243], v[4:7]
	v_mfma_f32_16x16x32_bf16 v[0:3], v[190:193], v[240:243], v[0:3]
	v_mfma_f32_16x16x32_bf16 v[54:57], v[186:189], v[220:223], v[54:57]
	v_mfma_f32_16x16x32_bf16 v[50:53], v[194:197], v[220:223], v[50:53]
	v_mfma_f32_16x16x32_bf16 v[38:41], v[186:189], v[228:231], v[38:41]
	v_mfma_f32_16x16x32_bf16 v[34:37], v[194:197], v[228:231], v[34:37]
	v_mfma_f32_16x16x32_bf16 v[20:23], v[186:189], v[236:239], v[20:23]
	v_mfma_f32_16x16x32_bf16 v[16:19], v[194:197], v[236:239], v[16:19]
	v_mfma_f32_16x16x32_bf16 v[4:7], v[186:189], v[244:247], v[4:7]
	v_mfma_f32_16x16x32_bf16 v[0:3], v[194:197], v[244:247], v[0:3]
	s_setprio 0
	s_barrier
	s_add_i32 s60, 0, 0x18000
	v_add_u32_e32 v32, s60, v149
	s_add_i32 s61, 0, 0x1c000
	ds_read_b128 v[142:145], v32
	ds_read_b128 v[152:155], v32 offset:1024
	ds_read_b128 v[156:159], v32 offset:2048
	ds_read_b128 v[160:163], v32 offset:3072
	v_add_u32_e32 v32, s61, v149
	ds_read_b128 v[164:167], v32
	ds_read_b128 v[186:189], v32 offset:1024
	ds_read_b128 v[190:193], v32 offset:2048
	ds_read_b128 v[194:197], v32 offset:3072
	s_add_u32 s30, s30, 0x80000
	s_addc_u32 s31, s31, 0
	s_mov_b32 m0, s48
	v_lshl_add_u64 v[250:251], s[30:31], 0, v[136:137]
	ds_read_b128 v[212:215], v151 offset:32768
	ds_read_b128 v[220:223], v151 offset:33792
	ds_read_b128 v[224:227], v151 offset:34816
	ds_read_b128 v[228:231], v151 offset:35840
	ds_read_b128 v[232:235], v151 offset:36864
	ds_read_b128 v[236:239], v151 offset:37888
	ds_read_b128 v[240:243], v151 offset:38912
	ds_read_b128 v[244:247], v151 offset:39936
	global_load_lds_dwordx4 v[250:251], off
	v_lshl_add_u64 v[250:251], s[30:31], 0, v[132:133]
	s_mov_b32 m0, s49
	s_nop 0
	global_load_lds_dwordx4 v[250:251], off
	s_waitcnt vmcnt(8)
	s_waitcnt lgkmcnt(0)
	.p2align	3
	s_setprio 1
	s_barrier
	v_mfma_f32_16x16x32_bf16 v[126:129], v[142:145], v[212:215], v[126:129]
	v_mfma_f32_16x16x32_bf16 v[122:125], v[156:159], v[212:215], v[122:125]
	v_mfma_f32_16x16x32_bf16 v[110:113], v[142:145], v[224:227], v[110:113]
	v_mfma_f32_16x16x32_bf16 v[106:109], v[156:159], v[224:227], v[106:109]
	v_mfma_f32_16x16x32_bf16 v[94:97], v[142:145], v[232:235], v[94:97]
	v_mfma_f32_16x16x32_bf16 v[90:93], v[156:159], v[232:235], v[90:93]
	v_mfma_f32_16x16x32_bf16 v[78:81], v[142:145], v[240:243], v[78:81]
	v_mfma_f32_16x16x32_bf16 v[74:77], v[156:159], v[240:243], v[74:77]
	v_mfma_f32_16x16x32_bf16 v[126:129], v[152:155], v[220:223], v[126:129]
	v_mfma_f32_16x16x32_bf16 v[122:125], v[160:163], v[220:223], v[122:125]
	v_mfma_f32_16x16x32_bf16 v[110:113], v[152:155], v[228:231], v[110:113]
	v_mfma_f32_16x16x32_bf16 v[106:109], v[160:163], v[228:231], v[106:109]
	v_mfma_f32_16x16x32_bf16 v[94:97], v[152:155], v[236:239], v[94:97]
	v_mfma_f32_16x16x32_bf16 v[90:93], v[160:163], v[236:239], v[90:93]
	v_mfma_f32_16x16x32_bf16 v[78:81], v[152:155], v[244:247], v[78:81]
	v_mfma_f32_16x16x32_bf16 v[74:77], v[160:163], v[244:247], v[74:77]
	v_mfma_f32_16x16x32_bf16 v[118:121], v[164:167], v[212:215], v[118:121]
	v_mfma_f32_16x16x32_bf16 v[114:117], v[190:193], v[212:215], v[114:117]
	v_mfma_f32_16x16x32_bf16 v[102:105], v[164:167], v[224:227], v[102:105]
	v_mfma_f32_16x16x32_bf16 v[98:101], v[190:193], v[224:227], v[98:101]
	v_mfma_f32_16x16x32_bf16 v[86:89], v[164:167], v[232:235], v[86:89]
	v_mfma_f32_16x16x32_bf16 v[82:85], v[190:193], v[232:235], v[82:85]
	v_mfma_f32_16x16x32_bf16 v[70:73], v[164:167], v[240:243], v[70:73]
	v_mfma_f32_16x16x32_bf16 v[66:69], v[190:193], v[240:243], v[66:69]
	v_mfma_f32_16x16x32_bf16 v[118:121], v[186:189], v[220:223], v[118:121]
	v_mfma_f32_16x16x32_bf16 v[114:117], v[194:197], v[220:223], v[114:117]
	v_mfma_f32_16x16x32_bf16 v[102:105], v[186:189], v[228:231], v[102:105]
	v_mfma_f32_16x16x32_bf16 v[98:101], v[194:197], v[228:231], v[98:101]
	v_mfma_f32_16x16x32_bf16 v[86:89], v[186:189], v[236:239], v[86:89]
	v_mfma_f32_16x16x32_bf16 v[82:85], v[194:197], v[236:239], v[82:85]
	v_mfma_f32_16x16x32_bf16 v[70:73], v[186:189], v[244:247], v[70:73]
	v_mfma_f32_16x16x32_bf16 v[66:69], v[194:197], v[244:247], v[66:69]
	s_setprio 0
	s_barrier
; #define PG8_STAGE(bufoff, gbase, voff) do { _Pragma("unroll") for (int _i = 0; _i < 2; ++_i) \
;         __builtin_amdgcn_global_load_lds((const unsigned*)((const char*)(gbase) + (voff)[_i]), (PG8_LAS unsigned*)(lds + (bufoff) + ldsw + _i * 8192), 16, 0, 0); } while (0)
; #define PG8_LDA(dst, b, h) do { _Pragma("unroll") for (int m = 0; m < 4; ++m) _Pragma("unroll") for (int k = 0; k < 2; ++k) dst[m][k] = *(const PG8_LAS bf16x8*)(lds + PG8_SA(b, h) + aoff + m * 2048 + k * 1024); } while (0)
; #define PG8_LDB(dst, b, h) do { _Pragma("unroll") for (int n = 0; n < 2; ++n) _Pragma("unroll") for (int k = 0; k < 2; ++k) dst[n][k] = *(const PG8_LAS bf16x8*)(lds + PG8_SB(b, h) + boff + n * 2048 + k * 1024); } while (0)
; #define PG8_MMA(ai, bj, At, Bt) do { __builtin_amdgcn_s_setprio(1); _Pragma("unroll") for (int m = 0; m < 4; ++m) _Pragma("unroll") for (int n = 0; n < 2; ++n) _Pragma("unroll") for (int k = 0; k < 2; ++k) \
;         acc[ai][bj][m][n] = __builtin_amdgcn_mfma_f32_16x16x32_bf16(Bt[n][k], At[m][k], acc[ai][bj][m][n], 0, 0, 0); __builtin_amdgcn_s_setprio(0); } while (0)
; template <class Epi, class Sched, bool ALIGN_EPI = false, bool SP2 = false>
; __device__ __forceinline__ void gemm_phase(PG8_LAS unsigned char* lds, const Gemm g, const Sched& S, const Epi& E, int tid_in) {
;     ...
;             if constexpr (SP2) {
;             PG8_LDB(B0, 0, 0); PG8_LDB(B1, 0, 1); PG8_SCHED; PG8_LDA(At, 0, 0); PG8_STAGE(PG8_SA(1, 1), a1 + hstep, voffA);
;             PG8_WAIT_V(8); PG8_WAIT_L(0); PG8_BAR; PG8_MMA(0, 0, At, B0); PG8_MMA(0, 1, At, B1); PG8_BAR; PG8_SCHED;
;             PG8_LDA(At, 0, 1); PG8_STAGE(PG8_SB(0, 0), b2, voffB); PG8_STAGE(PG8_SB(0, 1), b2 + hstep, voffB); PG8_STAGE(PG8_SA(0, 0), a2, voffA);
;             PG8_WAIT_V(8); PG8_WAIT_L(0); PG8_BAR; PG8_MMA(1, 0, At, B0); PG8_MMA(1, 1, At, B1); PG8_BAR; PG8_SCHED;
;             PG8_LDB(B0, 1, 0); PG8_LDB(B1, 1, 1); PG8_SCHED; PG8_LDA(At, 1, 0); PG8_STAGE(PG8_SA(0, 1), a2 + hstep, voffA);
;             PG8_WAIT_V(8); PG8_WAIT_L(0); PG8_BAR; PG8_MMA(0, 0, At, B0); PG8_MMA(0, 1, At, B1); PG8_BAR; PG8_SCHED;
;             PG8_LDA(At, 1, 1); PG8_STAGE(PG8_SB(1, 0), b3, voffB); PG8_STAGE(PG8_SB(1, 1), b3 + hstep, voffB); PG8_STAGE(PG8_SA(1, 0), a3, voffA);
;             PG8_WAIT_V(8); PG8_WAIT_L(0); PG8_BAR; PG8_MMA(1, 0, At, B0); PG8_MMA(1, 1, At, B1); PG8_BAR; PG8_SCHED;
	s_add_i32 s30, s60, s39
	v_lshl_add_u64 v[146:147], v[146:147], 0, s[74:75]
	s_mov_b32 m0, s30
	ds_read_b128 v[212:215], v151 offset:49152
	ds_read_b128 v[220:223], v151 offset:50176
	ds_read_b128 v[224:227], v151 offset:51200
	ds_read_b128 v[228:231], v151 offset:52224
	ds_read_b128 v[232:235], v151 offset:53248
	ds_read_b128 v[236:239], v151 offset:54272
	ds_read_b128 v[240:243], v151 offset:55296
	ds_read_b128 v[244:247], v151 offset:56320
	global_load_lds_dwordx4 v[146:147], off
	s_add_i32 m0, s30, 0x2000
	s_add_u32 s28, s28, 0x80080
	v_lshl_add_u64 v[146:147], v[168:169], 0, s[74:75]
	s_addc_u32 s29, s29, 0
	s_add_i32 s30, s61, s39
	global_load_lds_dwordx4 v[146:147], off
	v_lshl_add_u64 v[146:147], s[28:29], 0, v[134:135]
	s_mov_b32 m0, s30
	s_nop 0
	global_load_lds_dwordx4 v[146:147], off
	v_lshl_add_u64 v[146:147], s[28:29], 0, v[130:131]
	s_add_i32 m0, s30, 0x2000
	s_nop 0
	global_load_lds_dwordx4 v[146:147], off
	v_lshl_add_u64 v[146:147], v[216:217], 0, s[74:75]
	s_mov_b32 m0, s50
	s_nop 0
	global_load_lds_dwordx4 v[146:147], off
	v_lshl_add_u64 v[146:147], v[248:249], 0, s[74:75]
	s_mov_b32 m0, s51
	s_nop 0
	global_load_lds_dwordx4 v[146:147], off
	s_waitcnt vmcnt(8)
	s_waitcnt lgkmcnt(0)
	.p2align	3
	s_setprio 1
	s_barrier
	v_mfma_f32_16x16x32_bf16 v[62:65], v[142:145], v[212:215], v[62:65]
	v_mfma_f32_16x16x32_bf16 v[58:61], v[156:159], v[212:215], v[58:61]
	v_mfma_f32_16x16x32_bf16 v[46:49], v[142:145], v[224:227], v[46:49]
	v_mfma_f32_16x16x32_bf16 v[42:45], v[156:159], v[224:227], v[42:45]
	v_mfma_f32_16x16x32_bf16 v[28:31], v[142:145], v[232:235], v[28:31]
	v_mfma_f32_16x16x32_bf16 v[24:27], v[156:159], v[232:235], v[24:27]
	v_mfma_f32_16x16x32_bf16 v[12:15], v[142:145], v[240:243], v[12:15]
	v_mfma_f32_16x16x32_bf16 v[8:11], v[156:159], v[240:243], v[8:11]
	v_mfma_f32_16x16x32_bf16 v[62:65], v[152:155], v[220:223], v[62:65]
	v_mfma_f32_16x16x32_bf16 v[58:61], v[160:163], v[220:223], v[58:61]
	v_mfma_f32_16x16x32_bf16 v[46:49], v[152:155], v[228:231], v[46:49]
	v_mfma_f32_16x16x32_bf16 v[42:45], v[160:163], v[228:231], v[42:45]
	v_mfma_f32_16x16x32_bf16 v[28:31], v[152:155], v[236:239], v[28:31]
	v_mfma_f32_16x16x32_bf16 v[24:27], v[160:163], v[236:239], v[24:27]
	v_mfma_f32_16x16x32_bf16 v[12:15], v[152:155], v[244:247], v[12:15]
	v_mfma_f32_16x16x32_bf16 v[8:11], v[160:163], v[244:247], v[8:11]
	v_mfma_f32_16x16x32_bf16 v[54:57], v[164:167], v[212:215], v[54:57]
	v_mfma_f32_16x16x32_bf16 v[50:53], v[190:193], v[212:215], v[50:53]
	v_mfma_f32_16x16x32_bf16 v[38:41], v[164:167], v[224:227], v[38:41]
	v_mfma_f32_16x16x32_bf16 v[34:37], v[190:193], v[224:227], v[34:37]
	v_mfma_f32_16x16x32_bf16 v[20:23], v[164:167], v[232:235], v[20:23]
	v_mfma_f32_16x16x32_bf16 v[16:19], v[190:193], v[232:235], v[16:19]
	v_mfma_f32_16x16x32_bf16 v[4:7], v[164:167], v[240:243], v[4:7]
	v_mfma_f32_16x16x32_bf16 v[0:3], v[190:193], v[240:243], v[0:3]
	v_mfma_f32_16x16x32_bf16 v[54:57], v[186:189], v[220:223], v[54:57]
	v_mfma_f32_16x16x32_bf16 v[50:53], v[194:197], v[220:223], v[50:53]
	v_mfma_f32_16x16x32_bf16 v[38:41], v[186:189], v[228:231], v[38:41]
	v_mfma_f32_16x16x32_bf16 v[34:37], v[194:197], v[228:231], v[34:37]
	v_mfma_f32_16x16x32_bf16 v[20:23], v[186:189], v[236:239], v[20:23]
	v_mfma_f32_16x16x32_bf16 v[16:19], v[194:197], v[236:239], v[16:19]
	v_mfma_f32_16x16x32_bf16 v[4:7], v[186:189], v[244:247], v[4:7]
	v_mfma_f32_16x16x32_bf16 v[0:3], v[194:197], v[244:247], v[0:3]
	s_setprio 0
	s_barrier
	s_add_i32 s59, s59, 2
	s_add_u32 s6, s6, 0x100
	s_addc_u32 s7, s7, 0
	s_add_u32 s58, s58, 0x100
	s_addc_u32 s47, s47, 0
	s_cmp_gt_u32 s59, 29
	s_cbranch_scc0 .LBB0_59
	s_and_b64 vcc, exec, s[16:17]
	s_cbranch_vccz .LBB0_62
	s_barrier

; #define PG8_STAGE(bufoff, gbase, voff) do { _Pragma("unroll") for (int _i = 0; _i < 2; ++_i) \
;         __builtin_amdgcn_global_load_lds((const unsigned*)((const char*)(gbase) + (voff)[_i]), (PG8_LAS unsigned*)(lds + (bufoff) + ldsw + _i * 8192), 16, 0, 0); } while (0)
; #define PG8_LDA(dst, b, h) do { _Pragma("unroll") for (int m = 0; m < 4; ++m) _Pragma("unroll") for (int k = 0; k < 2; ++k) dst[m][k] = *(const PG8_LAS bf16x8*)(lds + PG8_SA(b, h) + aoff + m * 2048 + k * 1024); } while (0)
; #define PG8_LDB(dst, b, h) do { _Pragma("unroll") for (int n = 0; n < 2; ++n) _Pragma("unroll") for (int k = 0; k < 2; ++k) dst[n][k] = *(const PG8_LAS bf16x8*)(lds + PG8_SB(b, h) + boff + n * 2048 + k * 1024); } while (0)
; #define PG8_MMA(ai, bj, At, Bt) do { __builtin_amdgcn_s_setprio(1); _Pragma("unroll") for (int m = 0; m < 4; ++m) _Pragma("unroll") for (int n = 0; n < 2; ++n) _Pragma("unroll") for (int k = 0; k < 2; ++k) \
;         acc[ai][bj][m][n] = __builtin_amdgcn_mfma_f32_16x16x32_bf16(Bt[n][k], At[m][k], acc[ai][bj][m][n], 0, 0, 0); __builtin_amdgcn_s_setprio(0); } while (0)
; template <class Epi, class Sched, bool ALIGN_EPI = false, bool SP2 = false>
; __device__ __forceinline__ void gemm_phase(PG8_LAS unsigned char* lds, const Gemm g, const Sched& S, const Epi& E, int tid_in) {
;     ...
;             if constexpr (SP2) {
;             PG8_LDB(B0, 0, 0); PG8_LDB(B1, 0, 1); PG8_SCHED; PG8_LDA(At, 0, 0); PG8_STAGE(PG8_SA(1, 1), a1 + hstep, voffA);
;             PG8_WAIT_V(8); PG8_WAIT_L(0); PG8_BAR; PG8_MMA(0, 0, At, B0); PG8_MMA(0, 1, At, B1); PG8_BAR; PG8_SCHED;
;             PG8_LDA(At, 0, 1); PG8_STAGE(PG8_SB(0, 0), b2, voffB); PG8_STAGE(PG8_SB(0, 1), b2 + hstep, voffB); PG8_STAGE(PG8_SA(0, 0), a2, voffA);
;             PG8_WAIT_V(8); PG8_WAIT_L(0); PG8_BAR; PG8_MMA(1, 0, At, B0); PG8_MMA(1, 1, At, B1); PG8_BAR; PG8_SCHED;
;             PG8_LDB(B0, 1, 0); PG8_LDB(B1, 1, 1); PG8_SCHED; PG8_LDA(At, 1, 0); PG8_STAGE(PG8_SA(0, 1), a2 + hstep, voffA);
;             PG8_WAIT_V(8); PG8_WAIT_L(0); PG8_BAR; PG8_MMA(0, 0, At, B0); PG8_MMA(0, 1, At, B1); PG8_BAR; PG8_SCHED;
;             PG8_LDA(At, 1, 1); PG8_STAGE(PG8_SB(1, 0), b3, voffB); PG8_STAGE(PG8_SB(1, 1), b3 + hstep, voffB); PG8_STAGE(PG8_SA(1, 0), a3, voffA);
;             PG8_WAIT_V(8); PG8_WAIT_L(0); PG8_BAR; PG8_MMA(1, 0, At, B0); PG8_MMA(1, 1, At, B1); PG8_BAR; PG8_SCHED;
.LBB0_349:
	s_add_u32 s26, s24, 0x100
	s_addc_u32 s27, s25, 0
	s_add_i32 s60, 0, 0x10000
	s_cmp_eq_u32 s59, 28
	s_cselect_b32 s31, s19, s27
	s_cselect_b32 s30, s45, s26
	s_cselect_b32 s29, s17, s58
	s_cselect_b32 s28, s57, s47
	s_add_i32 s61, 0, 0x14000
	v_add_u32_e32 v152, s60, v141
	v_add_u32_e32 v168, s61, v141
	ds_read_b128 v[136:139], v152
	ds_read_b128 v[144:147], v152 offset:1024
	ds_read_b128 v[148:151], v152 offset:2048
	ds_read_b128 v[152:155], v152 offset:3072
	ds_read_b128 v[156:159], v168
	ds_read_b128 v[160:163], v168 offset:1024
	ds_read_b128 v[164:167], v168 offset:2048
	ds_read_b128 v[186:189], v168 offset:3072
	v_lshl_add_u64 v[168:169], s[24:25], 0, v[132:133]
	s_add_i32 m0, s39, 0xc000
	ds_read_b128 v[190:193], v143
	ds_read_b128 v[194:197], v143 offset:1024
	ds_read_b128 v[212:215], v143 offset:2048
	ds_read_b128 v[220:223], v143 offset:3072
	ds_read_b128 v[224:227], v143 offset:4096
	ds_read_b128 v[228:231], v143 offset:5120
	ds_read_b128 v[232:235], v143 offset:6144
	ds_read_b128 v[236:239], v143 offset:7168
	global_load_lds_dwordx4 v[168:169], off
	v_lshl_add_u64 v[168:169], s[24:25], 0, v[134:135]
	s_add_i32 m0, s39, 0xe000
	s_nop 0
	global_load_lds_dwordx4 v[168:169], off
	s_waitcnt vmcnt(8)
	s_waitcnt lgkmcnt(0)
	.p2align	3
	s_setprio 1
	s_barrier
	v_mfma_f32_16x16x32_bf16 v[126:129], v[136:139], v[190:193], v[126:129]
	v_mfma_f32_16x16x32_bf16 v[122:125], v[148:151], v[190:193], v[122:125]
	v_mfma_f32_16x16x32_bf16 v[114:117], v[136:139], v[212:215], v[114:117]
	v_mfma_f32_16x16x32_bf16 v[110:113], v[148:151], v[212:215], v[110:113]
	v_mfma_f32_16x16x32_bf16 v[98:101], v[136:139], v[224:227], v[98:101]
	v_mfma_f32_16x16x32_bf16 v[94:97], v[148:151], v[224:227], v[94:97]
	v_mfma_f32_16x16x32_bf16 v[82:85], v[136:139], v[232:235], v[82:85]
	v_mfma_f32_16x16x32_bf16 v[78:81], v[148:151], v[232:235], v[78:81]
	v_mfma_f32_16x16x32_bf16 v[126:129], v[144:147], v[194:197], v[126:129]
	v_mfma_f32_16x16x32_bf16 v[122:125], v[152:155], v[194:197], v[122:125]
	v_mfma_f32_16x16x32_bf16 v[114:117], v[144:147], v[220:223], v[114:117]
	v_mfma_f32_16x16x32_bf16 v[110:113], v[152:155], v[220:223], v[110:113]
	v_mfma_f32_16x16x32_bf16 v[98:101], v[144:147], v[228:231], v[98:101]
	v_mfma_f32_16x16x32_bf16 v[94:97], v[152:155], v[228:231], v[94:97]
	v_mfma_f32_16x16x32_bf16 v[82:85], v[144:147], v[236:239], v[82:85]
	v_mfma_f32_16x16x32_bf16 v[78:81], v[152:155], v[236:239], v[78:81]
	v_mfma_f32_16x16x32_bf16 v[118:121], v[156:159], v[190:193], v[118:121]
	v_mfma_f32_16x16x32_bf16 v[106:109], v[164:167], v[190:193], v[106:109]
	v_mfma_f32_16x16x32_bf16 v[102:105], v[156:159], v[212:215], v[102:105]
	v_mfma_f32_16x16x32_bf16 v[90:93], v[164:167], v[212:215], v[90:93]
	v_mfma_f32_16x16x32_bf16 v[86:89], v[156:159], v[224:227], v[86:89]
	v_mfma_f32_16x16x32_bf16 v[74:77], v[164:167], v[224:227], v[74:77]
	v_mfma_f32_16x16x32_bf16 v[70:73], v[156:159], v[232:235], v[70:73]
	v_mfma_f32_16x16x32_bf16 v[66:69], v[164:167], v[232:235], v[66:69]
	v_mfma_f32_16x16x32_bf16 v[118:121], v[160:163], v[194:197], v[118:121]
	v_mfma_f32_16x16x32_bf16 v[106:109], v[186:189], v[194:197], v[106:109]
	v_mfma_f32_16x16x32_bf16 v[102:105], v[160:163], v[220:223], v[102:105]
	v_mfma_f32_16x16x32_bf16 v[90:93], v[186:189], v[220:223], v[90:93]
	v_mfma_f32_16x16x32_bf16 v[86:89], v[160:163], v[228:231], v[86:89]
	v_mfma_f32_16x16x32_bf16 v[74:77], v[186:189], v[228:231], v[74:77]
	v_mfma_f32_16x16x32_bf16 v[70:73], v[160:163], v[236:239], v[70:73]
	v_mfma_f32_16x16x32_bf16 v[66:69], v[186:189], v[236:239], v[66:69]
	s_setprio 0
	s_barrier
	s_add_i32 s24, s60, s4
	v_lshl_add_u64 v[168:169], s[28:29], 0, v[32:33]
	s_mov_b32 m0, s24
	ds_read_b128 v[190:193], v143 offset:16384
	ds_read_b128 v[194:197], v143 offset:17408
	ds_read_b128 v[212:215], v143 offset:18432
	ds_read_b128 v[220:223], v143 offset:19456
	ds_read_b128 v[224:227], v143 offset:20480
	ds_read_b128 v[228:231], v143 offset:21504
	ds_read_b128 v[232:235], v143 offset:22528
	ds_read_b128 v[236:239], v143 offset:23552
	global_load_lds_dwordx4 v[168:169], off
	s_add_i32 m0, s24, 0x2000
	s_add_u32 s24, s28, 0x80000
	v_lshl_add_u64 v[216:217], s[28:29], 0, v[130:131]
	s_addc_u32 s25, s29, 0
	s_add_i32 s60, s61, s4
	global_load_lds_dwordx4 v[216:217], off
	v_lshl_add_u64 v[240:241], s[24:25], 0, v[32:33]
	s_mov_b32 m0, s60
	v_lshl_add_u64 v[242:243], s[30:31], 0, v[130:131]
	global_load_lds_dwordx4 v[240:241], off
	v_lshl_add_u64 v[240:241], s[24:25], 0, v[130:131]
	s_add_i32 m0, s60, 0x2000
	s_nop 0
	global_load_lds_dwordx4 v[240:241], off
	v_lshl_add_u64 v[240:241], s[30:31], 0, v[32:33]
	s_mov_b32 m0, s39
	s_nop 0
	global_load_lds_dwordx4 v[240:241], off
	s_mov_b32 m0, s42
	s_nop 0
	global_load_lds_dwordx4 v[242:243], off
	s_waitcnt vmcnt(8)
	s_waitcnt lgkmcnt(0)
	.p2align	3
	s_setprio 1
	s_barrier
; #define PG8_STAGE(bufoff, gbase, voff) do { _Pragma("unroll") for (int _i = 0; _i < 2; ++_i) \
;         __builtin_amdgcn_global_load_lds((const unsigned*)((const char*)(gbase) + (voff)[_i]), (PG8_LAS unsigned*)(lds + (bufoff) + ldsw + _i * 8192), 16, 0, 0); } while (0)
; #define PG8_LDA(dst, b, h) do { _Pragma("unroll") for (int m = 0; m < 4; ++m) _Pragma("unroll") for (int k = 0; k < 2; ++k) dst[m][k] = *(const PG8_LAS bf16x8*)(lds + PG8_SA(b, h) + aoff + m * 2048 + k * 1024); } while (0)
; #define PG8_LDB(dst, b, h) do { _Pragma("unroll") for (int n = 0; n < 2; ++n) _Pragma("unroll") for (int k = 0; k < 2; ++k) dst[n][k] = *(const PG8_LAS bf16x8*)(lds + PG8_SB(b, h) + boff + n * 2048 + k * 1024); } while (0)
; #define PG8_MMA(ai, bj, At, Bt) do { __builtin_amdgcn_s_setprio(1); _Pragma("unroll") for (int m = 0; m < 4; ++m) _Pragma("unroll") for (int n = 0; n < 2; ++n) _Pragma("unroll") for (int k = 0; k < 2; ++k) \
;         acc[ai][bj][m][n] = __builtin_amdgcn_mfma_f32_16x16x32_bf16(Bt[n][k], At[m][k], acc[ai][bj][m][n], 0, 0, 0); __builtin_amdgcn_s_setprio(0); } while (0)
; template <class Epi, class Sched, bool ALIGN_EPI = false, bool SP2 = false>
; __device__ __forceinline__ void gemm_phase(PG8_LAS unsigned char* lds, const Gemm g, const Sched& S, const Epi& E, int tid_in) {
;     ...
;             if constexpr (SP2) {
;             PG8_LDB(B0, 0, 0); PG8_LDB(B1, 0, 1); PG8_SCHED; PG8_LDA(At, 0, 0); PG8_STAGE(PG8_SA(1, 1), a1 + hstep, voffA);
;             PG8_WAIT_V(8); PG8_WAIT_L(0); PG8_BAR; PG8_MMA(0, 0, At, B0); PG8_MMA(0, 1, At, B1); PG8_BAR; PG8_SCHED;
;             PG8_LDA(At, 0, 1); PG8_STAGE(PG8_SB(0, 0), b2, voffB); PG8_STAGE(PG8_SB(0, 1), b2 + hstep, voffB); PG8_STAGE(PG8_SA(0, 0), a2, voffA);
;             PG8_WAIT_V(8); PG8_WAIT_L(0); PG8_BAR; PG8_MMA(1, 0, At, B0); PG8_MMA(1, 1, At, B1); PG8_BAR; PG8_SCHED;
;             PG8_LDB(B0, 1, 0); PG8_LDB(B1, 1, 1); PG8_SCHED; PG8_LDA(At, 1, 0); PG8_STAGE(PG8_SA(0, 1), a2 + hstep, voffA);
;             PG8_WAIT_V(8); PG8_WAIT_L(0); PG8_BAR; PG8_MMA(0, 0, At, B0); PG8_MMA(0, 1, At, B1); PG8_BAR; PG8_SCHED;
;             PG8_LDA(At, 1, 1); PG8_STAGE(PG8_SB(1, 0), b3, voffB); PG8_STAGE(PG8_SB(1, 1), b3 + hstep, voffB); PG8_STAGE(PG8_SA(1, 0), a3, voffA);
;             PG8_WAIT_V(8); PG8_WAIT_L(0); PG8_BAR; PG8_MMA(1, 0, At, B0); PG8_MMA(1, 1, At, B1); PG8_BAR; PG8_SCHED;
	v_mfma_f32_16x16x32_bf16 v[62:65], v[136:139], v[190:193], v[62:65]
	v_mfma_f32_16x16x32_bf16 v[58:61], v[148:151], v[190:193], v[58:61]
	v_mfma_f32_16x16x32_bf16 v[50:53], v[136:139], v[212:215], v[50:53]
	v_mfma_f32_16x16x32_bf16 v[46:49], v[148:151], v[212:215], v[46:49]
	v_mfma_f32_16x16x32_bf16 v[34:37], v[136:139], v[224:227], v[34:37]
	v_mfma_f32_16x16x32_bf16 v[28:31], v[148:151], v[224:227], v[28:31]
	v_mfma_f32_16x16x32_bf16 v[16:19], v[136:139], v[232:235], v[16:19]
	v_mfma_f32_16x16x32_bf16 v[12:15], v[148:151], v[232:235], v[12:15]
	v_mfma_f32_16x16x32_bf16 v[62:65], v[144:147], v[194:197], v[62:65]
	v_mfma_f32_16x16x32_bf16 v[58:61], v[152:155], v[194:197], v[58:61]
	v_mfma_f32_16x16x32_bf16 v[50:53], v[144:147], v[220:223], v[50:53]
	v_mfma_f32_16x16x32_bf16 v[46:49], v[152:155], v[220:223], v[46:49]
	v_mfma_f32_16x16x32_bf16 v[34:37], v[144:147], v[228:231], v[34:37]
	v_mfma_f32_16x16x32_bf16 v[28:31], v[152:155], v[228:231], v[28:31]
	v_mfma_f32_16x16x32_bf16 v[16:19], v[144:147], v[236:239], v[16:19]
	v_mfma_f32_16x16x32_bf16 v[12:15], v[152:155], v[236:239], v[12:15]
	v_mfma_f32_16x16x32_bf16 v[54:57], v[156:159], v[190:193], v[54:57]
	v_mfma_f32_16x16x32_bf16 v[42:45], v[164:167], v[190:193], v[42:45]
	v_mfma_f32_16x16x32_bf16 v[38:41], v[156:159], v[212:215], v[38:41]
	v_mfma_f32_16x16x32_bf16 v[24:27], v[164:167], v[212:215], v[24:27]
	v_mfma_f32_16x16x32_bf16 v[20:23], v[156:159], v[224:227], v[20:23]
	v_mfma_f32_16x16x32_bf16 v[8:11], v[164:167], v[224:227], v[8:11]
	v_mfma_f32_16x16x32_bf16 v[4:7], v[156:159], v[232:235], v[4:7]
	v_mfma_f32_16x16x32_bf16 v[0:3], v[164:167], v[232:235], v[0:3]
	v_mfma_f32_16x16x32_bf16 v[54:57], v[160:163], v[194:197], v[54:57]
	v_mfma_f32_16x16x32_bf16 v[42:45], v[186:189], v[194:197], v[42:45]
	v_mfma_f32_16x16x32_bf16 v[38:41], v[160:163], v[220:223], v[38:41]
	v_mfma_f32_16x16x32_bf16 v[24:27], v[186:189], v[220:223], v[24:27]
	v_mfma_f32_16x16x32_bf16 v[20:23], v[160:163], v[228:231], v[20:23]
	v_mfma_f32_16x16x32_bf16 v[8:11], v[186:189], v[228:231], v[8:11]
	v_mfma_f32_16x16x32_bf16 v[4:7], v[160:163], v[236:239], v[4:7]
	v_mfma_f32_16x16x32_bf16 v[0:3], v[186:189], v[236:239], v[0:3]
	s_setprio 0
	s_barrier
	s_add_i32 s60, 0, 0x18000
	s_add_i32 s61, 0, 0x1c000
	v_add_u32_e32 v152, s60, v141
	v_add_u32_e32 v170, s61, v141
	ds_read_b128 v[136:139], v152
	ds_read_b128 v[144:147], v152 offset:1024
	ds_read_b128 v[148:151], v152 offset:2048
	ds_read_b128 v[152:155], v152 offset:3072
	ds_read_b128 v[156:159], v170
	ds_read_b128 v[160:163], v170 offset:1024
	ds_read_b128 v[164:167], v170 offset:2048
	ds_read_b128 v[186:189], v170 offset:3072
	s_add_u32 s24, s30, 0x80000
	s_addc_u32 s25, s31, 0
	s_mov_b32 m0, s43
	v_lshl_add_u64 v[244:245], s[24:25], 0, v[32:33]
	ds_read_b128 v[190:193], v143 offset:32768
	ds_read_b128 v[194:197], v143 offset:33792
	ds_read_b128 v[212:215], v143 offset:34816
	ds_read_b128 v[220:223], v143 offset:35840
	ds_read_b128 v[224:227], v143 offset:36864
	ds_read_b128 v[228:231], v143 offset:37888
	ds_read_b128 v[232:235], v143 offset:38912
	ds_read_b128 v[236:239], v143 offset:39936
	global_load_lds_dwordx4 v[244:245], off
	v_lshl_add_u64 v[244:245], s[24:25], 0, v[130:131]
	s_mov_b32 m0, s48
	s_nop 0
	global_load_lds_dwordx4 v[244:245], off
	s_waitcnt vmcnt(8)
	s_waitcnt lgkmcnt(0)
	.p2align	3
	s_setprio 1
	s_barrier
	v_mfma_f32_16x16x32_bf16 v[126:129], v[136:139], v[190:193], v[126:129]
	v_mfma_f32_16x16x32_bf16 v[122:125], v[148:151], v[190:193], v[122:125]
	v_mfma_f32_16x16x32_bf16 v[114:117], v[136:139], v[212:215], v[114:117]
	v_mfma_f32_16x16x32_bf16 v[110:113], v[148:151], v[212:215], v[110:113]
	v_mfma_f32_16x16x32_bf16 v[98:101], v[136:139], v[224:227], v[98:101]
	v_mfma_f32_16x16x32_bf16 v[94:97], v[148:151], v[224:227], v[94:97]
	v_mfma_f32_16x16x32_bf16 v[82:85], v[136:139], v[232:235], v[82:85]
	v_mfma_f32_16x16x32_bf16 v[78:81], v[148:151], v[232:235], v[78:81]
	v_mfma_f32_16x16x32_bf16 v[126:129], v[144:147], v[194:197], v[126:129]
	v_mfma_f32_16x16x32_bf16 v[122:125], v[152:155], v[194:197], v[122:125]
	v_mfma_f32_16x16x32_bf16 v[114:117], v[144:147], v[220:223], v[114:117]
	v_mfma_f32_16x16x32_bf16 v[110:113], v[152:155], v[220:223], v[110:113]
	v_mfma_f32_16x16x32_bf16 v[98:101], v[144:147], v[228:231], v[98:101]
	v_mfma_f32_16x16x32_bf16 v[94:97], v[152:155], v[228:231], v[94:97]
	v_mfma_f32_16x16x32_bf16 v[82:85], v[144:147], v[236:239], v[82:85]
	v_mfma_f32_16x16x32_bf16 v[78:81], v[152:155], v[236:239], v[78:81]
	v_mfma_f32_16x16x32_bf16 v[118:121], v[156:159], v[190:193], v[118:121]
	v_mfma_f32_16x16x32_bf16 v[106:109], v[164:167], v[190:193], v[106:109]
	v_mfma_f32_16x16x32_bf16 v[102:105], v[156:159], v[212:215], v[102:105]
	v_mfma_f32_16x16x32_bf16 v[90:93], v[164:167], v[212:215], v[90:93]
	v_mfma_f32_16x16x32_bf16 v[86:89], v[156:159], v[224:227], v[86:89]
	v_mfma_f32_16x16x32_bf16 v[74:77], v[164:167], v[224:227], v[74:77]
	v_mfma_f32_16x16x32_bf16 v[70:73], v[156:159], v[232:235], v[70:73]
	v_mfma_f32_16x16x32_bf16 v[66:69], v[164:167], v[232:235], v[66:69]
	v_mfma_f32_16x16x32_bf16 v[118:121], v[160:163], v[194:197], v[118:121]
	v_mfma_f32_16x16x32_bf16 v[106:109], v[186:189], v[194:197], v[106:109]
	v_mfma_f32_16x16x32_bf16 v[102:105], v[160:163], v[220:223], v[102:105]
	v_mfma_f32_16x16x32_bf16 v[90:93], v[186:189], v[220:223], v[90:93]
	v_mfma_f32_16x16x32_bf16 v[86:89], v[160:163], v[228:231], v[86:89]
	v_mfma_f32_16x16x32_bf16 v[74:77], v[186:189], v[228:231], v[74:77]
	v_mfma_f32_16x16x32_bf16 v[70:73], v[160:163], v[236:239], v[70:73]
	v_mfma_f32_16x16x32_bf16 v[66:69], v[186:189], v[236:239], v[66:69]
	s_setprio 0
	s_barrier
; #define PG8_STAGE(bufoff, gbase, voff) do { _Pragma("unroll") for (int _i = 0; _i < 2; ++_i) \
;         __builtin_amdgcn_global_load_lds((const unsigned*)((const char*)(gbase) + (voff)[_i]), (PG8_LAS unsigned*)(lds + (bufoff) + ldsw + _i * 8192), 16, 0, 0); } while (0)
; #define PG8_LDA(dst, b, h) do { _Pragma("unroll") for (int m = 0; m < 4; ++m) _Pragma("unroll") for (int k = 0; k < 2; ++k) dst[m][k] = *(const PG8_LAS bf16x8*)(lds + PG8_SA(b, h) + aoff + m * 2048 + k * 1024); } while (0)
; #define PG8_LDB(dst, b, h) do { _Pragma("unroll") for (int n = 0; n < 2; ++n) _Pragma("unroll") for (int k = 0; k < 2; ++k) dst[n][k] = *(const PG8_LAS bf16x8*)(lds + PG8_SB(b, h) + boff + n * 2048 + k * 1024); } while (0)
; #define PG8_MMA(ai, bj, At, Bt) do { __builtin_amdgcn_s_setprio(1); _Pragma("unroll") for (int m = 0; m < 4; ++m) _Pragma("unroll") for (int n = 0; n < 2; ++n) _Pragma("unroll") for (int k = 0; k < 2; ++k) \
;         acc[ai][bj][m][n] = __builtin_amdgcn_mfma_f32_16x16x32_bf16(Bt[n][k], At[m][k], acc[ai][bj][m][n], 0, 0, 0); __builtin_amdgcn_s_setprio(0); } while (0)
; template <class Epi, class Sched, bool ALIGN_EPI = false, bool SP2 = false>
; __device__ __forceinline__ void gemm_phase(PG8_LAS unsigned char* lds, const Gemm g, const Sched& S, const Epi& E, int tid_in) {
;     ...
;             if constexpr (SP2) {
;             PG8_LDB(B0, 0, 0); PG8_LDB(B1, 0, 1); PG8_SCHED; PG8_LDA(At, 0, 0); PG8_STAGE(PG8_SA(1, 1), a1 + hstep, voffA);
;             PG8_WAIT_V(8); PG8_WAIT_L(0); PG8_BAR; PG8_MMA(0, 0, At, B0); PG8_MMA(0, 1, At, B1); PG8_BAR; PG8_SCHED;
;             PG8_LDA(At, 0, 1); PG8_STAGE(PG8_SB(0, 0), b2, voffB); PG8_STAGE(PG8_SB(0, 1), b2 + hstep, voffB); PG8_STAGE(PG8_SA(0, 0), a2, voffA);
;             PG8_WAIT_V(8); PG8_WAIT_L(0); PG8_BAR; PG8_MMA(1, 0, At, B0); PG8_MMA(1, 1, At, B1); PG8_BAR; PG8_SCHED;
;             PG8_LDB(B0, 1, 0); PG8_LDB(B1, 1, 1); PG8_SCHED; PG8_LDA(At, 1, 0); PG8_STAGE(PG8_SA(0, 1), a2 + hstep, voffA);
;             PG8_WAIT_V(8); PG8_WAIT_L(0); PG8_BAR; PG8_MMA(0, 0, At, B0); PG8_MMA(0, 1, At, B1); PG8_BAR; PG8_SCHED;
;             PG8_LDA(At, 1, 1); PG8_STAGE(PG8_SB(1, 0), b3, voffB); PG8_STAGE(PG8_SB(1, 1), b3 + hstep, voffB); PG8_STAGE(PG8_SA(1, 0), a3, voffA);
;             PG8_WAIT_V(8); PG8_WAIT_L(0); PG8_BAR; PG8_MMA(1, 0, At, B0); PG8_MMA(1, 1, At, B1); PG8_BAR; PG8_SCHED;
	s_add_i32 s24, s60, s4
	v_lshl_add_u64 v[168:169], v[168:169], 0, s[74:75]
	s_mov_b32 m0, s24
	ds_read_b128 v[190:193], v143 offset:49152
	ds_read_b128 v[194:197], v143 offset:50176
	ds_read_b128 v[212:215], v143 offset:51200
	ds_read_b128 v[220:223], v143 offset:52224
	ds_read_b128 v[224:227], v143 offset:53248
	ds_read_b128 v[228:231], v143 offset:54272
	ds_read_b128 v[232:235], v143 offset:55296
	ds_read_b128 v[236:239], v143 offset:56320
	global_load_lds_dwordx4 v[168:169], off
	s_add_i32 m0, s24, 0x2000
	s_add_u32 s24, s28, 0x80080
	v_lshl_add_u64 v[168:169], v[216:217], 0, s[74:75]
	s_addc_u32 s25, s29, 0
	s_add_i32 s28, s61, s4
	global_load_lds_dwordx4 v[168:169], off
	v_lshl_add_u64 v[168:169], s[24:25], 0, v[32:33]
	s_mov_b32 m0, s28
	s_nop 0
	global_load_lds_dwordx4 v[168:169], off
	v_lshl_add_u64 v[168:169], s[24:25], 0, v[130:131]
	s_add_i32 m0, s28, 0x2000
	s_nop 0
	global_load_lds_dwordx4 v[168:169], off
	v_lshl_add_u64 v[168:169], v[240:241], 0, s[74:75]
	s_mov_b32 m0, s49
	s_nop 0
	global_load_lds_dwordx4 v[168:169], off
	v_lshl_add_u64 v[168:169], v[242:243], 0, s[74:75]
	s_mov_b32 m0, s51
	s_nop 0
	global_load_lds_dwordx4 v[168:169], off
	s_waitcnt vmcnt(8)
	s_waitcnt lgkmcnt(0)
	.p2align	3
	s_setprio 1
	s_barrier
	v_mfma_f32_16x16x32_bf16 v[62:65], v[136:139], v[190:193], v[62:65]
	v_mfma_f32_16x16x32_bf16 v[58:61], v[148:151], v[190:193], v[58:61]
	v_mfma_f32_16x16x32_bf16 v[50:53], v[136:139], v[212:215], v[50:53]
	v_mfma_f32_16x16x32_bf16 v[46:49], v[148:151], v[212:215], v[46:49]
	v_mfma_f32_16x16x32_bf16 v[34:37], v[136:139], v[224:227], v[34:37]
	v_mfma_f32_16x16x32_bf16 v[28:31], v[148:151], v[224:227], v[28:31]
	v_mfma_f32_16x16x32_bf16 v[16:19], v[136:139], v[232:235], v[16:19]
	v_mfma_f32_16x16x32_bf16 v[12:15], v[148:151], v[232:235], v[12:15]
	v_mfma_f32_16x16x32_bf16 v[62:65], v[144:147], v[194:197], v[62:65]
	v_mfma_f32_16x16x32_bf16 v[58:61], v[152:155], v[194:197], v[58:61]
	v_mfma_f32_16x16x32_bf16 v[50:53], v[144:147], v[220:223], v[50:53]
	v_mfma_f32_16x16x32_bf16 v[46:49], v[152:155], v[220:223], v[46:49]
	v_mfma_f32_16x16x32_bf16 v[34:37], v[144:147], v[228:231], v[34:37]
	v_mfma_f32_16x16x32_bf16 v[28:31], v[152:155], v[228:231], v[28:31]
	v_mfma_f32_16x16x32_bf16 v[16:19], v[144:147], v[236:239], v[16:19]
	v_mfma_f32_16x16x32_bf16 v[12:15], v[152:155], v[236:239], v[12:15]
	v_mfma_f32_16x16x32_bf16 v[54:57], v[156:159], v[190:193], v[54:57]
	v_mfma_f32_16x16x32_bf16 v[42:45], v[164:167], v[190:193], v[42:45]
	v_mfma_f32_16x16x32_bf16 v[38:41], v[156:159], v[212:215], v[38:41]
	v_mfma_f32_16x16x32_bf16 v[24:27], v[164:167], v[212:215], v[24:27]
	v_mfma_f32_16x16x32_bf16 v[20:23], v[156:159], v[224:227], v[20:23]
	v_mfma_f32_16x16x32_bf16 v[8:11], v[164:167], v[224:227], v[8:11]
	v_mfma_f32_16x16x32_bf16 v[4:7], v[156:159], v[232:235], v[4:7]
	v_mfma_f32_16x16x32_bf16 v[0:3], v[164:167], v[232:235], v[0:3]
	v_mfma_f32_16x16x32_bf16 v[54:57], v[160:163], v[194:197], v[54:57]
	v_mfma_f32_16x16x32_bf16 v[42:45], v[186:189], v[194:197], v[42:45]
	v_mfma_f32_16x16x32_bf16 v[38:41], v[160:163], v[220:223], v[38:41]
	v_mfma_f32_16x16x32_bf16 v[24:27], v[186:189], v[220:223], v[24:27]
	v_mfma_f32_16x16x32_bf16 v[20:23], v[160:163], v[228:231], v[20:23]
	v_mfma_f32_16x16x32_bf16 v[8:11], v[186:189], v[228:231], v[8:11]
	v_mfma_f32_16x16x32_bf16 v[4:7], v[160:163], v[236:239], v[4:7]
	v_mfma_f32_16x16x32_bf16 v[0:3], v[186:189], v[236:239], v[0:3]
	s_setprio 0
	s_barrier
	s_add_i32 s59, s59, 2
	s_add_u32 s47, s47, 0x100
	s_addc_u32 s58, s58, 0
	s_cmp_gt_u32 s59, 29
	s_mov_b64 s[24:25], s[26:27]
	s_cbranch_scc0 .LBB0_349
	s_and_b64 vcc, exec, s[14:15]
	s_cbranch_vccz .LBB0_352
	s_barrier

; #define PG8_STAGE(bufoff, gbase, voff) do { _Pragma("unroll") for (int _i = 0; _i < 2; ++_i) \
;         __builtin_amdgcn_global_load_lds((const unsigned*)((const char*)(gbase) + (voff)[_i]), (PG8_LAS unsigned*)(lds + (bufoff) + ldsw + _i * 8192), 16, 0, 0); } while (0)
; #define PG8_LDA(dst, b, h) do { _Pragma("unroll") for (int m = 0; m < 4; ++m) _Pragma("unroll") for (int k = 0; k < 2; ++k) dst[m][k] = *(const PG8_LAS bf16x8*)(lds + PG8_SA(b, h) + aoff + m * 2048 + k * 1024); } while (0)
; #define PG8_LDB(dst, b, h) do { _Pragma("unroll") for (int n = 0; n < 2; ++n) _Pragma("unroll") for (int k = 0; k < 2; ++k) dst[n][k] = *(const PG8_LAS bf16x8*)(lds + PG8_SB(b, h) + boff + n * 2048 + k * 1024); } while (0)
; #define PG8_MMA(ai, bj, At, Bt) do { __builtin_amdgcn_s_setprio(1); _Pragma("unroll") for (int m = 0; m < 4; ++m) _Pragma("unroll") for (int n = 0; n < 2; ++n) _Pragma("unroll") for (int k = 0; k < 2; ++k) \
;         acc[ai][bj][m][n] = __builtin_amdgcn_mfma_f32_16x16x32_bf16(Bt[n][k], At[m][k], acc[ai][bj][m][n], 0, 0, 0); __builtin_amdgcn_s_setprio(0); } while (0)
; template <class Epi, class Sched, bool ALIGN_EPI = false, bool SP2 = false>
; __device__ __forceinline__ void gemm_phase(PG8_LAS unsigned char* lds, const Gemm g, const Sched& S, const Epi& E, int tid_in) {
;     ...
;             if constexpr (SP2) {
;             PG8_LDB(B0, 0, 0); PG8_LDB(B1, 0, 1); PG8_SCHED; PG8_LDA(At, 0, 0); PG8_STAGE(PG8_SA(1, 1), a1 + hstep, voffA);
;             PG8_WAIT_V(8); PG8_WAIT_L(0); PG8_BAR; PG8_MMA(0, 0, At, B0); PG8_MMA(0, 1, At, B1); PG8_BAR; PG8_SCHED;
;             PG8_LDA(At, 0, 1); PG8_STAGE(PG8_SB(0, 0), b2, voffB); PG8_STAGE(PG8_SB(0, 1), b2 + hstep, voffB); PG8_STAGE(PG8_SA(0, 0), a2, voffA);
;             PG8_WAIT_V(8); PG8_WAIT_L(0); PG8_BAR; PG8_MMA(1, 0, At, B0); PG8_MMA(1, 1, At, B1); PG8_BAR; PG8_SCHED;
;             PG8_LDB(B0, 1, 0); PG8_LDB(B1, 1, 1); PG8_SCHED; PG8_LDA(At, 1, 0); PG8_STAGE(PG8_SA(0, 1), a2 + hstep, voffA);
;             PG8_WAIT_V(8); PG8_WAIT_L(0); PG8_BAR; PG8_MMA(0, 0, At, B0); PG8_MMA(0, 1, At, B1); PG8_BAR; PG8_SCHED;
;             PG8_LDA(At, 1, 1); PG8_STAGE(PG8_SB(1, 0), b3, voffB); PG8_STAGE(PG8_SB(1, 1), b3 + hstep, voffB); PG8_STAGE(PG8_SA(1, 0), a3, voffA);
;             PG8_WAIT_V(8); PG8_WAIT_L(0); PG8_BAR; PG8_MMA(1, 0, At, B0); PG8_MMA(1, 1, At, B1); PG8_BAR; PG8_SCHED;
.LBB0_479:
	s_add_u32 s16, s56, 0xfff80080
	s_addc_u32 s17, s57, -1
	s_add_i32 s18, 0, 0x10000
	s_cmp_eq_u32 s82, 28
	s_cselect_b32 s63, s71, s17
	s_cselect_b32 s62, vcc_lo, s16
	s_cselect_b32 s61, s59, s77
	s_cselect_b32 s60, vcc_hi, s47
	s_add_i32 s19, 0, 0x14000
	v_add_u32_e32 v78, s18, v172
	v_add_u32_e32 v102, s19, v172
	ds_read_b128 v[66:69], v78
	ds_read_b128 v[70:73], v78 offset:1024
	ds_read_b128 v[74:77], v78 offset:2048
	ds_read_b128 v[78:81], v78 offset:3072
	ds_read_b128 v[86:89], v102
	ds_read_b128 v[90:93], v102 offset:1024
	ds_read_b128 v[94:97], v102 offset:2048
	ds_read_b128 v[102:105], v102 offset:3072
	v_lshl_add_u64 v[196:197], s[56:57], 0, v[192:193]
	s_add_i32 m0, s68, 0xc000
	ds_read_b128 v[162:165], v217
	ds_read_b128 v[166:169], v217 offset:1024
	ds_read_b128 v[220:223], v217 offset:2048
	ds_read_b128 v[224:227], v217 offset:3072
	ds_read_b128 v[228:231], v217 offset:4096
	ds_read_b128 v[232:235], v217 offset:5120
	ds_read_b128 v[236:239], v217 offset:6144
	ds_read_b128 v[240:243], v217 offset:7168
	global_load_lds_dwordx4 v[196:197], off
	v_lshl_add_u64 v[196:197], s[56:57], 0, v[194:195]
	s_add_i32 m0, s68, 0xe000
	s_nop 0
	global_load_lds_dwordx4 v[196:197], off
	s_waitcnt vmcnt(8)
	s_waitcnt lgkmcnt(0)
	.p2align	3
	s_setprio 1
	s_barrier
	v_mfma_f32_16x16x32_bf16 v[150:153], v[66:69], v[162:165], v[150:153]
	v_mfma_f32_16x16x32_bf16 v[146:149], v[74:77], v[162:165], v[146:149]
	v_mfma_f32_16x16x32_bf16 v[138:141], v[66:69], v[220:223], v[138:141]
	v_mfma_f32_16x16x32_bf16 v[130:133], v[74:77], v[220:223], v[130:133]
	v_mfma_f32_16x16x32_bf16 v[122:125], v[66:69], v[228:231], v[122:125]
	v_mfma_f32_16x16x32_bf16 v[110:113], v[74:77], v[228:231], v[110:113]
	v_mfma_f32_16x16x32_bf16 v[114:117], v[66:69], v[236:239], v[114:117]
	v_mfma_f32_16x16x32_bf16 v[98:101], v[74:77], v[236:239], v[98:101]
	v_mfma_f32_16x16x32_bf16 v[150:153], v[70:73], v[166:169], v[150:153]
	v_mfma_f32_16x16x32_bf16 v[146:149], v[78:81], v[166:169], v[146:149]
	v_mfma_f32_16x16x32_bf16 v[138:141], v[70:73], v[224:227], v[138:141]
	v_mfma_f32_16x16x32_bf16 v[130:133], v[78:81], v[224:227], v[130:133]
	v_mfma_f32_16x16x32_bf16 v[122:125], v[70:73], v[232:235], v[122:125]
	v_mfma_f32_16x16x32_bf16 v[110:113], v[78:81], v[232:235], v[110:113]
	v_mfma_f32_16x16x32_bf16 v[114:117], v[70:73], v[240:243], v[114:117]
	v_mfma_f32_16x16x32_bf16 v[98:101], v[78:81], v[240:243], v[98:101]
	v_mfma_f32_16x16x32_bf16 v[158:161], v[86:89], v[162:165], v[158:161]
	v_mfma_f32_16x16x32_bf16 v[154:157], v[94:97], v[162:165], v[154:157]
	v_mfma_f32_16x16x32_bf16 v[142:145], v[86:89], v[220:223], v[142:145]
	v_mfma_f32_16x16x32_bf16 v[134:137], v[94:97], v[220:223], v[134:137]
	v_mfma_f32_16x16x32_bf16 v[126:129], v[86:89], v[228:231], v[126:129]
	v_mfma_f32_16x16x32_bf16 v[118:121], v[94:97], v[228:231], v[118:121]
	v_mfma_f32_16x16x32_bf16 v[106:109], v[86:89], v[236:239], v[106:109]
	v_mfma_f32_16x16x32_bf16 v[82:85], v[94:97], v[236:239], v[82:85]
	v_mfma_f32_16x16x32_bf16 v[158:161], v[90:93], v[166:169], v[158:161]
	v_mfma_f32_16x16x32_bf16 v[154:157], v[102:105], v[166:169], v[154:157]
	v_mfma_f32_16x16x32_bf16 v[142:145], v[90:93], v[224:227], v[142:145]
	v_mfma_f32_16x16x32_bf16 v[134:137], v[102:105], v[224:227], v[134:137]
	v_mfma_f32_16x16x32_bf16 v[126:129], v[90:93], v[232:235], v[126:129]
	v_mfma_f32_16x16x32_bf16 v[118:121], v[102:105], v[232:235], v[118:121]
	v_mfma_f32_16x16x32_bf16 v[106:109], v[90:93], v[240:243], v[106:109]
	v_mfma_f32_16x16x32_bf16 v[82:85], v[102:105], v[240:243], v[82:85]
	s_setprio 0
	s_barrier
	s_add_i32 s16, s18, s67
	v_lshl_add_u64 v[196:197], s[60:61], 0, v[32:33]
	s_mov_b32 m0, s16
	ds_read_b128 v[162:165], v217 offset:16384
	ds_read_b128 v[166:169], v217 offset:17408
	ds_read_b128 v[220:223], v217 offset:18432
	ds_read_b128 v[224:227], v217 offset:19456
	ds_read_b128 v[228:231], v217 offset:20480
	ds_read_b128 v[232:235], v217 offset:21504
	ds_read_b128 v[236:239], v217 offset:22528
	ds_read_b128 v[240:243], v217 offset:23552
	global_load_lds_dwordx4 v[196:197], off
	s_add_i32 m0, s16, 0x2000
	s_add_u32 s16, s60, 0x80000
	v_lshl_add_u64 v[244:245], s[60:61], 0, v[186:187]
	s_addc_u32 s17, s61, 0
	s_add_i32 s18, s19, s67
	global_load_lds_dwordx4 v[244:245], off
	v_lshl_add_u64 v[246:247], s[16:17], 0, v[32:33]
	s_mov_b32 m0, s18
	v_lshl_add_u64 v[248:249], s[62:63], 0, v[188:189]
	global_load_lds_dwordx4 v[246:247], off
	v_lshl_add_u64 v[246:247], s[16:17], 0, v[186:187]
	s_add_i32 m0, s18, 0x2000
	s_nop 0
	global_load_lds_dwordx4 v[246:247], off
	v_lshl_add_u64 v[246:247], s[62:63], 0, v[190:191]
	s_mov_b32 m0, s68
	s_nop 0
	global_load_lds_dwordx4 v[246:247], off
	s_mov_b32 m0, s14
	s_nop 0
	global_load_lds_dwordx4 v[248:249], off
	s_waitcnt vmcnt(8)
	s_waitcnt lgkmcnt(0)
	.p2align	3
	s_setprio 1
	s_barrier
; #define PG8_STAGE(bufoff, gbase, voff) do { _Pragma("unroll") for (int _i = 0; _i < 2; ++_i) \
;         __builtin_amdgcn_global_load_lds((const unsigned*)((const char*)(gbase) + (voff)[_i]), (PG8_LAS unsigned*)(lds + (bufoff) + ldsw + _i * 8192), 16, 0, 0); } while (0)
; #define PG8_LDA(dst, b, h) do { _Pragma("unroll") for (int m = 0; m < 4; ++m) _Pragma("unroll") for (int k = 0; k < 2; ++k) dst[m][k] = *(const PG8_LAS bf16x8*)(lds + PG8_SA(b, h) + aoff + m * 2048 + k * 1024); } while (0)
; #define PG8_LDB(dst, b, h) do { _Pragma("unroll") for (int n = 0; n < 2; ++n) _Pragma("unroll") for (int k = 0; k < 2; ++k) dst[n][k] = *(const PG8_LAS bf16x8*)(lds + PG8_SB(b, h) + boff + n * 2048 + k * 1024); } while (0)
; #define PG8_MMA(ai, bj, At, Bt) do { __builtin_amdgcn_s_setprio(1); _Pragma("unroll") for (int m = 0; m < 4; ++m) _Pragma("unroll") for (int n = 0; n < 2; ++n) _Pragma("unroll") for (int k = 0; k < 2; ++k) \
;         acc[ai][bj][m][n] = __builtin_amdgcn_mfma_f32_16x16x32_bf16(Bt[n][k], At[m][k], acc[ai][bj][m][n], 0, 0, 0); __builtin_amdgcn_s_setprio(0); } while (0)
; template <class Epi, class Sched, bool ALIGN_EPI = false, bool SP2 = false>
; __device__ __forceinline__ void gemm_phase(PG8_LAS unsigned char* lds, const Gemm g, const Sched& S, const Epi& E, int tid_in) {
;     ...
;             if constexpr (SP2) {
;             PG8_LDB(B0, 0, 0); PG8_LDB(B1, 0, 1); PG8_SCHED; PG8_LDA(At, 0, 0); PG8_STAGE(PG8_SA(1, 1), a1 + hstep, voffA);
;             PG8_WAIT_V(8); PG8_WAIT_L(0); PG8_BAR; PG8_MMA(0, 0, At, B0); PG8_MMA(0, 1, At, B1); PG8_BAR; PG8_SCHED;
;             PG8_LDA(At, 0, 1); PG8_STAGE(PG8_SB(0, 0), b2, voffB); PG8_STAGE(PG8_SB(0, 1), b2 + hstep, voffB); PG8_STAGE(PG8_SA(0, 0), a2, voffA);
;             PG8_WAIT_V(8); PG8_WAIT_L(0); PG8_BAR; PG8_MMA(1, 0, At, B0); PG8_MMA(1, 1, At, B1); PG8_BAR; PG8_SCHED;
;             PG8_LDB(B0, 1, 0); PG8_LDB(B1, 1, 1); PG8_SCHED; PG8_LDA(At, 1, 0); PG8_STAGE(PG8_SA(0, 1), a2 + hstep, voffA);
;             PG8_WAIT_V(8); PG8_WAIT_L(0); PG8_BAR; PG8_MMA(0, 0, At, B0); PG8_MMA(0, 1, At, B1); PG8_BAR; PG8_SCHED;
;             PG8_LDA(At, 1, 1); PG8_STAGE(PG8_SB(1, 0), b3, voffB); PG8_STAGE(PG8_SB(1, 1), b3 + hstep, voffB); PG8_STAGE(PG8_SA(1, 0), a3, voffA);
;             PG8_WAIT_V(8); PG8_WAIT_L(0); PG8_BAR; PG8_MMA(1, 0, At, B0); PG8_MMA(1, 1, At, B1); PG8_BAR; PG8_SCHED;
	v_mfma_f32_16x16x32_bf16 v[54:57], v[66:69], v[162:165], v[54:57]
	v_mfma_f32_16x16x32_bf16 v[50:53], v[74:77], v[162:165], v[50:53]
	v_mfma_f32_16x16x32_bf16 v[42:45], v[66:69], v[220:223], v[42:45]
	v_mfma_f32_16x16x32_bf16 v[34:37], v[74:77], v[220:223], v[34:37]
	v_mfma_f32_16x16x32_bf16 v[24:27], v[66:69], v[228:231], v[24:27]
	v_mfma_f32_16x16x32_bf16 v[12:15], v[74:77], v[228:231], v[12:15]
	v_mfma_f32_16x16x32_bf16 v[16:19], v[66:69], v[236:239], v[16:19]
	v_mfma_f32_16x16x32_bf16 v[4:7], v[74:77], v[236:239], v[4:7]
	v_mfma_f32_16x16x32_bf16 v[54:57], v[70:73], v[166:169], v[54:57]
	v_mfma_f32_16x16x32_bf16 v[50:53], v[78:81], v[166:169], v[50:53]
	v_mfma_f32_16x16x32_bf16 v[42:45], v[70:73], v[224:227], v[42:45]
	v_mfma_f32_16x16x32_bf16 v[34:37], v[78:81], v[224:227], v[34:37]
	v_mfma_f32_16x16x32_bf16 v[24:27], v[70:73], v[232:235], v[24:27]
	v_mfma_f32_16x16x32_bf16 v[12:15], v[78:81], v[232:235], v[12:15]
	v_mfma_f32_16x16x32_bf16 v[16:19], v[70:73], v[240:243], v[16:19]
	v_mfma_f32_16x16x32_bf16 v[4:7], v[78:81], v[240:243], v[4:7]
	v_mfma_f32_16x16x32_bf16 v[62:65], v[86:89], v[162:165], v[62:65]
	v_mfma_f32_16x16x32_bf16 v[58:61], v[94:97], v[162:165], v[58:61]
	v_mfma_f32_16x16x32_bf16 v[46:49], v[86:89], v[220:223], v[46:49]
	v_mfma_f32_16x16x32_bf16 v[38:41], v[94:97], v[220:223], v[38:41]
	v_mfma_f32_16x16x32_bf16 v[28:31], v[86:89], v[228:231], v[28:31]
	v_mfma_f32_16x16x32_bf16 v[20:23], v[94:97], v[228:231], v[20:23]
	v_mfma_f32_16x16x32_bf16 v[8:11], v[86:89], v[236:239], v[8:11]
	v_mfma_f32_16x16x32_bf16 v[0:3], v[94:97], v[236:239], v[0:3]
	v_mfma_f32_16x16x32_bf16 v[62:65], v[90:93], v[166:169], v[62:65]
	v_mfma_f32_16x16x32_bf16 v[58:61], v[102:105], v[166:169], v[58:61]
	v_mfma_f32_16x16x32_bf16 v[46:49], v[90:93], v[224:227], v[46:49]
	v_mfma_f32_16x16x32_bf16 v[38:41], v[102:105], v[224:227], v[38:41]
	v_mfma_f32_16x16x32_bf16 v[28:31], v[90:93], v[232:235], v[28:31]
	v_mfma_f32_16x16x32_bf16 v[20:23], v[102:105], v[232:235], v[20:23]
	v_mfma_f32_16x16x32_bf16 v[8:11], v[90:93], v[240:243], v[8:11]
	v_mfma_f32_16x16x32_bf16 v[0:3], v[102:105], v[240:243], v[0:3]
	s_setprio 0
	s_barrier
	s_add_i32 s18, 0, 0x18000
	s_add_i32 s19, 0, 0x1c000
	v_add_u32_e32 v78, s18, v172
	v_add_u32_e32 v102, s19, v172
	ds_read_b128 v[66:69], v78
	ds_read_b128 v[70:73], v78 offset:1024
	ds_read_b128 v[74:77], v78 offset:2048
	ds_read_b128 v[78:81], v78 offset:3072
	ds_read_b128 v[86:89], v102
	ds_read_b128 v[90:93], v102 offset:1024
	ds_read_b128 v[94:97], v102 offset:2048
	ds_read_b128 v[102:105], v102 offset:3072
	s_add_u32 s16, s62, 0x80000
	s_addc_u32 s17, s63, 0
	s_mov_b32 m0, s15
	v_lshl_add_u64 v[250:251], s[16:17], 0, v[190:191]
	ds_read_b128 v[162:165], v217 offset:32768
	ds_read_b128 v[166:169], v217 offset:33792
	ds_read_b128 v[220:223], v217 offset:34816
	ds_read_b128 v[224:227], v217 offset:35840
	ds_read_b128 v[228:231], v217 offset:36864
	ds_read_b128 v[232:235], v217 offset:37888
	ds_read_b128 v[236:239], v217 offset:38912
	ds_read_b128 v[240:243], v217 offset:39936
	global_load_lds_dwordx4 v[250:251], off
	v_lshl_add_u64 v[250:251], s[16:17], 0, v[188:189]
	s_mov_b32 m0, s4
	s_nop 0
	global_load_lds_dwordx4 v[250:251], off
	s_waitcnt vmcnt(8)
	s_waitcnt lgkmcnt(0)
	.p2align	3
	s_setprio 1
	s_barrier
	v_mfma_f32_16x16x32_bf16 v[150:153], v[66:69], v[162:165], v[150:153]
	v_mfma_f32_16x16x32_bf16 v[146:149], v[74:77], v[162:165], v[146:149]
	v_mfma_f32_16x16x32_bf16 v[138:141], v[66:69], v[220:223], v[138:141]
	v_mfma_f32_16x16x32_bf16 v[130:133], v[74:77], v[220:223], v[130:133]
	v_mfma_f32_16x16x32_bf16 v[122:125], v[66:69], v[228:231], v[122:125]
	v_mfma_f32_16x16x32_bf16 v[110:113], v[74:77], v[228:231], v[110:113]
	v_mfma_f32_16x16x32_bf16 v[114:117], v[66:69], v[236:239], v[114:117]
	v_mfma_f32_16x16x32_bf16 v[98:101], v[74:77], v[236:239], v[98:101]
	v_mfma_f32_16x16x32_bf16 v[150:153], v[70:73], v[166:169], v[150:153]
	v_mfma_f32_16x16x32_bf16 v[146:149], v[78:81], v[166:169], v[146:149]
	v_mfma_f32_16x16x32_bf16 v[138:141], v[70:73], v[224:227], v[138:141]
	v_mfma_f32_16x16x32_bf16 v[130:133], v[78:81], v[224:227], v[130:133]
	v_mfma_f32_16x16x32_bf16 v[122:125], v[70:73], v[232:235], v[122:125]
	v_mfma_f32_16x16x32_bf16 v[110:113], v[78:81], v[232:235], v[110:113]
	v_mfma_f32_16x16x32_bf16 v[114:117], v[70:73], v[240:243], v[114:117]
	v_mfma_f32_16x16x32_bf16 v[98:101], v[78:81], v[240:243], v[98:101]
	v_mfma_f32_16x16x32_bf16 v[158:161], v[86:89], v[162:165], v[158:161]
	v_mfma_f32_16x16x32_bf16 v[154:157], v[94:97], v[162:165], v[154:157]
	v_mfma_f32_16x16x32_bf16 v[142:145], v[86:89], v[220:223], v[142:145]
	v_mfma_f32_16x16x32_bf16 v[134:137], v[94:97], v[220:223], v[134:137]
	v_mfma_f32_16x16x32_bf16 v[126:129], v[86:89], v[228:231], v[126:129]
	v_mfma_f32_16x16x32_bf16 v[118:121], v[94:97], v[228:231], v[118:121]
	v_mfma_f32_16x16x32_bf16 v[106:109], v[86:89], v[236:239], v[106:109]
	v_mfma_f32_16x16x32_bf16 v[82:85], v[94:97], v[236:239], v[82:85]
	v_mfma_f32_16x16x32_bf16 v[158:161], v[90:93], v[166:169], v[158:161]
	v_mfma_f32_16x16x32_bf16 v[154:157], v[102:105], v[166:169], v[154:157]
	v_mfma_f32_16x16x32_bf16 v[142:145], v[90:93], v[224:227], v[142:145]
	v_mfma_f32_16x16x32_bf16 v[134:137], v[102:105], v[224:227], v[134:137]
	v_mfma_f32_16x16x32_bf16 v[126:129], v[90:93], v[232:235], v[126:129]
	v_mfma_f32_16x16x32_bf16 v[118:121], v[102:105], v[232:235], v[118:121]
	v_mfma_f32_16x16x32_bf16 v[106:109], v[90:93], v[240:243], v[106:109]
	v_mfma_f32_16x16x32_bf16 v[82:85], v[102:105], v[240:243], v[82:85]
	s_setprio 0
	s_barrier
; #define PG8_STAGE(bufoff, gbase, voff) do { _Pragma("unroll") for (int _i = 0; _i < 2; ++_i) \
;         __builtin_amdgcn_global_load_lds((const unsigned*)((const char*)(gbase) + (voff)[_i]), (PG8_LAS unsigned*)(lds + (bufoff) + ldsw + _i * 8192), 16, 0, 0); } while (0)
; #define PG8_LDA(dst, b, h) do { _Pragma("unroll") for (int m = 0; m < 4; ++m) _Pragma("unroll") for (int k = 0; k < 2; ++k) dst[m][k] = *(const PG8_LAS bf16x8*)(lds + PG8_SA(b, h) + aoff + m * 2048 + k * 1024); } while (0)
; #define PG8_LDB(dst, b, h) do { _Pragma("unroll") for (int n = 0; n < 2; ++n) _Pragma("unroll") for (int k = 0; k < 2; ++k) dst[n][k] = *(const PG8_LAS bf16x8*)(lds + PG8_SB(b, h) + boff + n * 2048 + k * 1024); } while (0)
; #define PG8_MMA(ai, bj, At, Bt) do { __builtin_amdgcn_s_setprio(1); _Pragma("unroll") for (int m = 0; m < 4; ++m) _Pragma("unroll") for (int n = 0; n < 2; ++n) _Pragma("unroll") for (int k = 0; k < 2; ++k) \
;         acc[ai][bj][m][n] = __builtin_amdgcn_mfma_f32_16x16x32_bf16(Bt[n][k], At[m][k], acc[ai][bj][m][n], 0, 0, 0); __builtin_amdgcn_s_setprio(0); } while (0)
; template <class Epi, class Sched, bool ALIGN_EPI = false, bool SP2 = false>
; __device__ __forceinline__ void gemm_phase(PG8_LAS unsigned char* lds, const Gemm g, const Sched& S, const Epi& E, int tid_in) {
;     ...
;             if constexpr (SP2) {
;             PG8_LDB(B0, 0, 0); PG8_LDB(B1, 0, 1); PG8_SCHED; PG8_LDA(At, 0, 0); PG8_STAGE(PG8_SA(1, 1), a1 + hstep, voffA);
;             PG8_WAIT_V(8); PG8_WAIT_L(0); PG8_BAR; PG8_MMA(0, 0, At, B0); PG8_MMA(0, 1, At, B1); PG8_BAR; PG8_SCHED;
;             PG8_LDA(At, 0, 1); PG8_STAGE(PG8_SB(0, 0), b2, voffB); PG8_STAGE(PG8_SB(0, 1), b2 + hstep, voffB); PG8_STAGE(PG8_SA(0, 0), a2, voffA);
;             PG8_WAIT_V(8); PG8_WAIT_L(0); PG8_BAR; PG8_MMA(1, 0, At, B0); PG8_MMA(1, 1, At, B1); PG8_BAR; PG8_SCHED;
;             PG8_LDB(B0, 1, 0); PG8_LDB(B1, 1, 1); PG8_SCHED; PG8_LDA(At, 1, 0); PG8_STAGE(PG8_SA(0, 1), a2 + hstep, voffA);
;             PG8_WAIT_V(8); PG8_WAIT_L(0); PG8_BAR; PG8_MMA(0, 0, At, B0); PG8_MMA(0, 1, At, B1); PG8_BAR; PG8_SCHED;
;             PG8_LDA(At, 1, 1); PG8_STAGE(PG8_SB(1, 0), b3, voffB); PG8_STAGE(PG8_SB(1, 1), b3 + hstep, voffB); PG8_STAGE(PG8_SA(1, 0), a3, voffA);
;             PG8_WAIT_V(8); PG8_WAIT_L(0); PG8_BAR; PG8_MMA(1, 0, At, B0); PG8_MMA(1, 1, At, B1); PG8_BAR; PG8_SCHED;
	s_add_i32 s16, s18, s67
	v_lshl_add_u64 v[196:197], v[196:197], 0, s[74:75]
	s_mov_b32 m0, s16
	ds_read_b128 v[162:165], v217 offset:49152
	ds_read_b128 v[166:169], v217 offset:50176
	ds_read_b128 v[220:223], v217 offset:51200
	ds_read_b128 v[224:227], v217 offset:52224
	ds_read_b128 v[228:231], v217 offset:53248
	ds_read_b128 v[232:235], v217 offset:54272
	ds_read_b128 v[236:239], v217 offset:55296
	ds_read_b128 v[240:243], v217 offset:56320
	global_load_lds_dwordx4 v[196:197], off
	s_add_i32 m0, s16, 0x2000
	s_add_u32 s16, s60, 0x80080
	v_lshl_add_u64 v[196:197], v[244:245], 0, s[74:75]
	s_addc_u32 s17, s61, 0
	s_add_i32 s18, s19, s67
	global_load_lds_dwordx4 v[196:197], off
	v_lshl_add_u64 v[196:197], s[16:17], 0, v[32:33]
	s_mov_b32 m0, s18
	s_nop 0
	global_load_lds_dwordx4 v[196:197], off
	v_lshl_add_u64 v[196:197], s[16:17], 0, v[186:187]
	s_add_i32 m0, s18, 0x2000
	s_nop 0
	global_load_lds_dwordx4 v[196:197], off
	v_lshl_add_u64 v[196:197], v[246:247], 0, s[74:75]
	s_mov_b32 m0, s85
	s_nop 0
	global_load_lds_dwordx4 v[196:197], off
	v_lshl_add_u64 v[196:197], v[248:249], 0, s[74:75]
	s_mov_b32 m0, s80
	s_nop 0
	global_load_lds_dwordx4 v[196:197], off
	s_waitcnt vmcnt(8)
	s_waitcnt lgkmcnt(0)
	.p2align	3
	s_setprio 1
	s_barrier
	v_mfma_f32_16x16x32_bf16 v[54:57], v[66:69], v[162:165], v[54:57]
	v_mfma_f32_16x16x32_bf16 v[50:53], v[74:77], v[162:165], v[50:53]
	v_mfma_f32_16x16x32_bf16 v[42:45], v[66:69], v[220:223], v[42:45]
	v_mfma_f32_16x16x32_bf16 v[34:37], v[74:77], v[220:223], v[34:37]
	v_mfma_f32_16x16x32_bf16 v[24:27], v[66:69], v[228:231], v[24:27]
	v_mfma_f32_16x16x32_bf16 v[12:15], v[74:77], v[228:231], v[12:15]
	v_mfma_f32_16x16x32_bf16 v[16:19], v[66:69], v[236:239], v[16:19]
	v_mfma_f32_16x16x32_bf16 v[4:7], v[74:77], v[236:239], v[4:7]
	v_mfma_f32_16x16x32_bf16 v[54:57], v[70:73], v[166:169], v[54:57]
	v_mfma_f32_16x16x32_bf16 v[50:53], v[78:81], v[166:169], v[50:53]
	v_mfma_f32_16x16x32_bf16 v[42:45], v[70:73], v[224:227], v[42:45]
	v_mfma_f32_16x16x32_bf16 v[34:37], v[78:81], v[224:227], v[34:37]
	v_mfma_f32_16x16x32_bf16 v[24:27], v[70:73], v[232:235], v[24:27]
	v_mfma_f32_16x16x32_bf16 v[12:15], v[78:81], v[232:235], v[12:15]
	v_mfma_f32_16x16x32_bf16 v[16:19], v[70:73], v[240:243], v[16:19]
	v_mfma_f32_16x16x32_bf16 v[4:7], v[78:81], v[240:243], v[4:7]
	v_mfma_f32_16x16x32_bf16 v[62:65], v[86:89], v[162:165], v[62:65]
	v_mfma_f32_16x16x32_bf16 v[58:61], v[94:97], v[162:165], v[58:61]
	v_mfma_f32_16x16x32_bf16 v[46:49], v[86:89], v[220:223], v[46:49]
	v_mfma_f32_16x16x32_bf16 v[38:41], v[94:97], v[220:223], v[38:41]
	v_mfma_f32_16x16x32_bf16 v[28:31], v[86:89], v[228:231], v[28:31]
	v_mfma_f32_16x16x32_bf16 v[20:23], v[94:97], v[228:231], v[20:23]
	v_mfma_f32_16x16x32_bf16 v[8:11], v[86:89], v[236:239], v[8:11]
	v_mfma_f32_16x16x32_bf16 v[0:3], v[94:97], v[236:239], v[0:3]
	v_mfma_f32_16x16x32_bf16 v[62:65], v[90:93], v[166:169], v[62:65]
	v_mfma_f32_16x16x32_bf16 v[58:61], v[102:105], v[166:169], v[58:61]
	v_mfma_f32_16x16x32_bf16 v[46:49], v[90:93], v[224:227], v[46:49]
	v_mfma_f32_16x16x32_bf16 v[38:41], v[102:105], v[224:227], v[38:41]
	v_mfma_f32_16x16x32_bf16 v[28:31], v[90:93], v[232:235], v[28:31]
	v_mfma_f32_16x16x32_bf16 v[20:23], v[102:105], v[232:235], v[20:23]
	v_mfma_f32_16x16x32_bf16 v[8:11], v[90:93], v[240:243], v[8:11]
	v_mfma_f32_16x16x32_bf16 v[0:3], v[102:105], v[240:243], v[0:3]
	s_setprio 0
	s_barrier
	s_add_i32 s82, s82, 2
	s_add_u32 s56, s56, 0x100
	s_addc_u32 s57, s57, 0
	s_add_u32 s47, s47, 0x100
	s_addc_u32 s77, s77, 0
	s_cmp_gt_u32 s82, 29
	s_cbranch_scc0 .LBB0_479
	s_and_b64 vcc, exec, s[34:35]
	s_cbranch_vccz .LBB0_482
	s_barrier

; #define PG8_STAGE(bufoff, gbase, voff) do { _Pragma("unroll") for (int _i = 0; _i < 2; ++_i) \
;         __builtin_amdgcn_global_load_lds((const unsigned*)((const char*)(gbase) + (voff)[_i]), (PG8_LAS unsigned*)(lds + (bufoff) + ldsw + _i * 8192), 16, 0, 0); } while (0)
; #define PG8_LDA(dst, b, h) do { _Pragma("unroll") for (int m = 0; m < 4; ++m) _Pragma("unroll") for (int k = 0; k < 2; ++k) dst[m][k] = *(const PG8_LAS bf16x8*)(lds + PG8_SA(b, h) + aoff + m * 2048 + k * 1024); } while (0)
; #define PG8_LDB(dst, b, h) do { _Pragma("unroll") for (int n = 0; n < 2; ++n) _Pragma("unroll") for (int k = 0; k < 2; ++k) dst[n][k] = *(const PG8_LAS bf16x8*)(lds + PG8_SB(b, h) + boff + n * 2048 + k * 1024); } while (0)
; #define PG8_MMA(ai, bj, At, Bt) do { __builtin_amdgcn_s_setprio(1); _Pragma("unroll") for (int m = 0; m < 4; ++m) _Pragma("unroll") for (int n = 0; n < 2; ++n) _Pragma("unroll") for (int k = 0; k < 2; ++k) \
;         acc[ai][bj][m][n] = __builtin_amdgcn_mfma_f32_16x16x32_bf16(Bt[n][k], At[m][k], acc[ai][bj][m][n], 0, 0, 0); __builtin_amdgcn_s_setprio(0); } while (0)
; template <class Epi, class Sched, bool ALIGN_EPI = false, bool SP2 = false>
; __device__ __forceinline__ void gemm_phase(PG8_LAS unsigned char* lds, const Gemm g, const Sched& S, const Epi& E, int tid_in) {
;     ...
;             if constexpr (SP2) {
;             PG8_LDB(B0, 0, 0); PG8_LDB(B1, 0, 1); PG8_SCHED; PG8_LDA(At, 0, 0); PG8_STAGE(PG8_SA(1, 1), a1 + hstep, voffA);
;             PG8_WAIT_V(8); PG8_WAIT_L(0); PG8_BAR; PG8_MMA(0, 0, At, B0); PG8_MMA(0, 1, At, B1); PG8_BAR; PG8_SCHED;
;             PG8_LDA(At, 0, 1); PG8_STAGE(PG8_SB(0, 0), b2, voffB); PG8_STAGE(PG8_SB(0, 1), b2 + hstep, voffB); PG8_STAGE(PG8_SA(0, 0), a2, voffA);
;             PG8_WAIT_V(8); PG8_WAIT_L(0); PG8_BAR; PG8_MMA(1, 0, At, B0); PG8_MMA(1, 1, At, B1); PG8_BAR; PG8_SCHED;
;             PG8_LDB(B0, 1, 0); PG8_LDB(B1, 1, 1); PG8_SCHED; PG8_LDA(At, 1, 0); PG8_STAGE(PG8_SA(0, 1), a2 + hstep, voffA);
;             PG8_WAIT_V(8); PG8_WAIT_L(0); PG8_BAR; PG8_MMA(0, 0, At, B0); PG8_MMA(0, 1, At, B1); PG8_BAR; PG8_SCHED;
;             PG8_LDA(At, 1, 1); PG8_STAGE(PG8_SB(1, 0), b3, voffB); PG8_STAGE(PG8_SB(1, 1), b3 + hstep, voffB); PG8_STAGE(PG8_SA(1, 0), a3, voffA);
;             PG8_WAIT_V(8); PG8_WAIT_L(0); PG8_BAR; PG8_MMA(1, 0, At, B0); PG8_MMA(1, 1, At, B1); PG8_BAR; PG8_SCHED;
.LBB0_625:
	s_add_u32 s26, s24, 0x100
	s_addc_u32 s27, s25, 0
	s_add_i32 s58, 0, 0x10000
	s_cmpk_eq_i32 s57, 0x54
	s_cselect_b32 s31, s7, s27
	s_cselect_b32 s30, s6, s26
	s_cselect_b32 s29, s23, s47
	s_cselect_b32 s28, s22, s45
	s_add_i32 s59, 0, 0x14000
	v_add_u32_e32 v152, s58, v141
	v_add_u32_e32 v168, s59, v141
	ds_read_b128 v[136:139], v152
	ds_read_b128 v[144:147], v152 offset:1024
	ds_read_b128 v[148:151], v152 offset:2048
	ds_read_b128 v[152:155], v152 offset:3072
	ds_read_b128 v[156:159], v168
	ds_read_b128 v[160:163], v168 offset:1024
	ds_read_b128 v[164:167], v168 offset:2048
	ds_read_b128 v[186:189], v168 offset:3072
	v_lshl_add_u64 v[168:169], s[24:25], 0, v[132:133]
	s_add_i32 m0, s38, 0xc000
	ds_read_b128 v[190:193], v143
	ds_read_b128 v[194:197], v143 offset:1024
	ds_read_b128 v[212:215], v143 offset:2048
	ds_read_b128 v[220:223], v143 offset:3072
	ds_read_b128 v[224:227], v143 offset:4096
	ds_read_b128 v[228:231], v143 offset:5120
	ds_read_b128 v[232:235], v143 offset:6144
	ds_read_b128 v[236:239], v143 offset:7168
	global_load_lds_dwordx4 v[168:169], off
	v_lshl_add_u64 v[168:169], s[24:25], 0, v[134:135]
	s_add_i32 m0, s38, 0xe000
	s_nop 0
	global_load_lds_dwordx4 v[168:169], off
	s_waitcnt vmcnt(8)
	s_waitcnt lgkmcnt(0)
	.p2align	3
	s_setprio 1
	s_barrier
	v_mfma_f32_16x16x32_bf16 v[126:129], v[136:139], v[190:193], v[126:129]
	v_mfma_f32_16x16x32_bf16 v[122:125], v[148:151], v[190:193], v[122:125]
	v_mfma_f32_16x16x32_bf16 v[114:117], v[136:139], v[212:215], v[114:117]
	v_mfma_f32_16x16x32_bf16 v[110:113], v[148:151], v[212:215], v[110:113]
	v_mfma_f32_16x16x32_bf16 v[98:101], v[136:139], v[224:227], v[98:101]
	v_mfma_f32_16x16x32_bf16 v[94:97], v[148:151], v[224:227], v[94:97]
	v_mfma_f32_16x16x32_bf16 v[82:85], v[136:139], v[232:235], v[82:85]
	v_mfma_f32_16x16x32_bf16 v[78:81], v[148:151], v[232:235], v[78:81]
	v_mfma_f32_16x16x32_bf16 v[126:129], v[144:147], v[194:197], v[126:129]
	v_mfma_f32_16x16x32_bf16 v[122:125], v[152:155], v[194:197], v[122:125]
	v_mfma_f32_16x16x32_bf16 v[114:117], v[144:147], v[220:223], v[114:117]
	v_mfma_f32_16x16x32_bf16 v[110:113], v[152:155], v[220:223], v[110:113]
	v_mfma_f32_16x16x32_bf16 v[98:101], v[144:147], v[228:231], v[98:101]
	v_mfma_f32_16x16x32_bf16 v[94:97], v[152:155], v[228:231], v[94:97]
	v_mfma_f32_16x16x32_bf16 v[82:85], v[144:147], v[236:239], v[82:85]
	v_mfma_f32_16x16x32_bf16 v[78:81], v[152:155], v[236:239], v[78:81]
	v_mfma_f32_16x16x32_bf16 v[118:121], v[156:159], v[190:193], v[118:121]
	v_mfma_f32_16x16x32_bf16 v[106:109], v[164:167], v[190:193], v[106:109]
	v_mfma_f32_16x16x32_bf16 v[102:105], v[156:159], v[212:215], v[102:105]
	v_mfma_f32_16x16x32_bf16 v[90:93], v[164:167], v[212:215], v[90:93]
	v_mfma_f32_16x16x32_bf16 v[86:89], v[156:159], v[224:227], v[86:89]
	v_mfma_f32_16x16x32_bf16 v[74:77], v[164:167], v[224:227], v[74:77]
	v_mfma_f32_16x16x32_bf16 v[70:73], v[156:159], v[232:235], v[70:73]
	v_mfma_f32_16x16x32_bf16 v[66:69], v[164:167], v[232:235], v[66:69]
	v_mfma_f32_16x16x32_bf16 v[118:121], v[160:163], v[194:197], v[118:121]
	v_mfma_f32_16x16x32_bf16 v[106:109], v[186:189], v[194:197], v[106:109]
	v_mfma_f32_16x16x32_bf16 v[102:105], v[160:163], v[220:223], v[102:105]
	v_mfma_f32_16x16x32_bf16 v[90:93], v[186:189], v[220:223], v[90:93]
	v_mfma_f32_16x16x32_bf16 v[86:89], v[160:163], v[228:231], v[86:89]
	v_mfma_f32_16x16x32_bf16 v[74:77], v[186:189], v[228:231], v[74:77]
	v_mfma_f32_16x16x32_bf16 v[70:73], v[160:163], v[236:239], v[70:73]
	v_mfma_f32_16x16x32_bf16 v[66:69], v[186:189], v[236:239], v[66:69]
	s_setprio 0
	s_barrier
	s_add_i32 s24, s58, s35
	v_lshl_add_u64 v[168:169], s[28:29], 0, v[32:33]
	s_mov_b32 m0, s24
	ds_read_b128 v[190:193], v143 offset:16384
	ds_read_b128 v[194:197], v143 offset:17408
	ds_read_b128 v[212:215], v143 offset:18432
	ds_read_b128 v[220:223], v143 offset:19456
	ds_read_b128 v[224:227], v143 offset:20480
	ds_read_b128 v[228:231], v143 offset:21504
	ds_read_b128 v[232:235], v143 offset:22528
	ds_read_b128 v[236:239], v143 offset:23552
	global_load_lds_dwordx4 v[168:169], off
	s_add_i32 m0, s24, 0x2000
	s_add_u32 s24, s28, 0x160000
	v_lshl_add_u64 v[216:217], s[28:29], 0, v[130:131]
	s_addc_u32 s25, s29, 0
	s_add_i32 s58, s59, s35
	global_load_lds_dwordx4 v[216:217], off
	v_lshl_add_u64 v[240:241], s[24:25], 0, v[32:33]
	s_mov_b32 m0, s58
	v_lshl_add_u64 v[242:243], s[30:31], 0, v[130:131]
	global_load_lds_dwordx4 v[240:241], off
	v_lshl_add_u64 v[240:241], s[24:25], 0, v[130:131]
	s_add_i32 m0, s58, 0x2000
	s_nop 0
	global_load_lds_dwordx4 v[240:241], off
	v_lshl_add_u64 v[240:241], s[30:31], 0, v[32:33]
	s_mov_b32 m0, s38
	s_nop 0
	global_load_lds_dwordx4 v[240:241], off
	s_mov_b32 m0, s39
	s_nop 0
	global_load_lds_dwordx4 v[242:243], off
	s_waitcnt vmcnt(8)
	s_waitcnt lgkmcnt(0)
	.p2align	3
	s_setprio 1
	s_barrier
; #define PG8_STAGE(bufoff, gbase, voff) do { _Pragma("unroll") for (int _i = 0; _i < 2; ++_i) \
;         __builtin_amdgcn_global_load_lds((const unsigned*)((const char*)(gbase) + (voff)[_i]), (PG8_LAS unsigned*)(lds + (bufoff) + ldsw + _i * 8192), 16, 0, 0); } while (0)
; #define PG8_LDA(dst, b, h) do { _Pragma("unroll") for (int m = 0; m < 4; ++m) _Pragma("unroll") for (int k = 0; k < 2; ++k) dst[m][k] = *(const PG8_LAS bf16x8*)(lds + PG8_SA(b, h) + aoff + m * 2048 + k * 1024); } while (0)
; #define PG8_LDB(dst, b, h) do { _Pragma("unroll") for (int n = 0; n < 2; ++n) _Pragma("unroll") for (int k = 0; k < 2; ++k) dst[n][k] = *(const PG8_LAS bf16x8*)(lds + PG8_SB(b, h) + boff + n * 2048 + k * 1024); } while (0)
; #define PG8_MMA(ai, bj, At, Bt) do { __builtin_amdgcn_s_setprio(1); _Pragma("unroll") for (int m = 0; m < 4; ++m) _Pragma("unroll") for (int n = 0; n < 2; ++n) _Pragma("unroll") for (int k = 0; k < 2; ++k) \
;         acc[ai][bj][m][n] = __builtin_amdgcn_mfma_f32_16x16x32_bf16(Bt[n][k], At[m][k], acc[ai][bj][m][n], 0, 0, 0); __builtin_amdgcn_s_setprio(0); } while (0)
; template <class Epi, class Sched, bool ALIGN_EPI = false, bool SP2 = false>
; __device__ __forceinline__ void gemm_phase(PG8_LAS unsigned char* lds, const Gemm g, const Sched& S, const Epi& E, int tid_in) {
;     ...
;             if constexpr (SP2) {
;             PG8_LDB(B0, 0, 0); PG8_LDB(B1, 0, 1); PG8_SCHED; PG8_LDA(At, 0, 0); PG8_STAGE(PG8_SA(1, 1), a1 + hstep, voffA);
;             PG8_WAIT_V(8); PG8_WAIT_L(0); PG8_BAR; PG8_MMA(0, 0, At, B0); PG8_MMA(0, 1, At, B1); PG8_BAR; PG8_SCHED;
;             PG8_LDA(At, 0, 1); PG8_STAGE(PG8_SB(0, 0), b2, voffB); PG8_STAGE(PG8_SB(0, 1), b2 + hstep, voffB); PG8_STAGE(PG8_SA(0, 0), a2, voffA);
;             PG8_WAIT_V(8); PG8_WAIT_L(0); PG8_BAR; PG8_MMA(1, 0, At, B0); PG8_MMA(1, 1, At, B1); PG8_BAR; PG8_SCHED;
;             PG8_LDB(B0, 1, 0); PG8_LDB(B1, 1, 1); PG8_SCHED; PG8_LDA(At, 1, 0); PG8_STAGE(PG8_SA(0, 1), a2 + hstep, voffA);
;             PG8_WAIT_V(8); PG8_WAIT_L(0); PG8_BAR; PG8_MMA(0, 0, At, B0); PG8_MMA(0, 1, At, B1); PG8_BAR; PG8_SCHED;
;             PG8_LDA(At, 1, 1); PG8_STAGE(PG8_SB(1, 0), b3, voffB); PG8_STAGE(PG8_SB(1, 1), b3 + hstep, voffB); PG8_STAGE(PG8_SA(1, 0), a3, voffA);
;             PG8_WAIT_V(8); PG8_WAIT_L(0); PG8_BAR; PG8_MMA(1, 0, At, B0); PG8_MMA(1, 1, At, B1); PG8_BAR; PG8_SCHED;
	v_mfma_f32_16x16x32_bf16 v[62:65], v[136:139], v[190:193], v[62:65]
	v_mfma_f32_16x16x32_bf16 v[58:61], v[148:151], v[190:193], v[58:61]
	v_mfma_f32_16x16x32_bf16 v[50:53], v[136:139], v[212:215], v[50:53]
	v_mfma_f32_16x16x32_bf16 v[46:49], v[148:151], v[212:215], v[46:49]
	v_mfma_f32_16x16x32_bf16 v[34:37], v[136:139], v[224:227], v[34:37]
	v_mfma_f32_16x16x32_bf16 v[28:31], v[148:151], v[224:227], v[28:31]
	v_mfma_f32_16x16x32_bf16 v[16:19], v[136:139], v[232:235], v[16:19]
	v_mfma_f32_16x16x32_bf16 v[12:15], v[148:151], v[232:235], v[12:15]
	v_mfma_f32_16x16x32_bf16 v[62:65], v[144:147], v[194:197], v[62:65]
	v_mfma_f32_16x16x32_bf16 v[58:61], v[152:155], v[194:197], v[58:61]
	v_mfma_f32_16x16x32_bf16 v[50:53], v[144:147], v[220:223], v[50:53]
	v_mfma_f32_16x16x32_bf16 v[46:49], v[152:155], v[220:223], v[46:49]
	v_mfma_f32_16x16x32_bf16 v[34:37], v[144:147], v[228:231], v[34:37]
	v_mfma_f32_16x16x32_bf16 v[28:31], v[152:155], v[228:231], v[28:31]
	v_mfma_f32_16x16x32_bf16 v[16:19], v[144:147], v[236:239], v[16:19]
	v_mfma_f32_16x16x32_bf16 v[12:15], v[152:155], v[236:239], v[12:15]
	v_mfma_f32_16x16x32_bf16 v[54:57], v[156:159], v[190:193], v[54:57]
	v_mfma_f32_16x16x32_bf16 v[42:45], v[164:167], v[190:193], v[42:45]
	v_mfma_f32_16x16x32_bf16 v[38:41], v[156:159], v[212:215], v[38:41]
	v_mfma_f32_16x16x32_bf16 v[24:27], v[164:167], v[212:215], v[24:27]
	v_mfma_f32_16x16x32_bf16 v[20:23], v[156:159], v[224:227], v[20:23]
	v_mfma_f32_16x16x32_bf16 v[8:11], v[164:167], v[224:227], v[8:11]
	v_mfma_f32_16x16x32_bf16 v[4:7], v[156:159], v[232:235], v[4:7]
	v_mfma_f32_16x16x32_bf16 v[0:3], v[164:167], v[232:235], v[0:3]
	v_mfma_f32_16x16x32_bf16 v[54:57], v[160:163], v[194:197], v[54:57]
	v_mfma_f32_16x16x32_bf16 v[42:45], v[186:189], v[194:197], v[42:45]
	v_mfma_f32_16x16x32_bf16 v[38:41], v[160:163], v[220:223], v[38:41]
	v_mfma_f32_16x16x32_bf16 v[24:27], v[186:189], v[220:223], v[24:27]
	v_mfma_f32_16x16x32_bf16 v[20:23], v[160:163], v[228:231], v[20:23]
	v_mfma_f32_16x16x32_bf16 v[8:11], v[186:189], v[228:231], v[8:11]
	v_mfma_f32_16x16x32_bf16 v[4:7], v[160:163], v[236:239], v[4:7]
	v_mfma_f32_16x16x32_bf16 v[0:3], v[186:189], v[236:239], v[0:3]
	s_setprio 0
	s_barrier
	s_add_i32 s58, 0, 0x18000
	s_add_i32 s59, 0, 0x1c000
	v_add_u32_e32 v152, s58, v141
	v_add_u32_e32 v170, s59, v141
	ds_read_b128 v[136:139], v152
	ds_read_b128 v[144:147], v152 offset:1024
	ds_read_b128 v[148:151], v152 offset:2048
	ds_read_b128 v[152:155], v152 offset:3072
	ds_read_b128 v[156:159], v170
	ds_read_b128 v[160:163], v170 offset:1024
	ds_read_b128 v[164:167], v170 offset:2048
	ds_read_b128 v[186:189], v170 offset:3072
	s_add_u32 s24, s30, 0x160000
	s_addc_u32 s25, s31, 0
	s_mov_b32 m0, s42
	v_lshl_add_u64 v[244:245], s[24:25], 0, v[32:33]
	ds_read_b128 v[190:193], v143 offset:32768
	ds_read_b128 v[194:197], v143 offset:33792
	ds_read_b128 v[212:215], v143 offset:34816
	ds_read_b128 v[220:223], v143 offset:35840
	ds_read_b128 v[224:227], v143 offset:36864
	ds_read_b128 v[228:231], v143 offset:37888
	ds_read_b128 v[232:235], v143 offset:38912
	ds_read_b128 v[236:239], v143 offset:39936
	global_load_lds_dwordx4 v[244:245], off
	v_lshl_add_u64 v[244:245], s[24:25], 0, v[130:131]
	s_mov_b32 m0, s43
	s_nop 0
	global_load_lds_dwordx4 v[244:245], off
	s_waitcnt vmcnt(8)
	s_waitcnt lgkmcnt(0)
	.p2align	3
	s_setprio 1
	s_barrier
	v_mfma_f32_16x16x32_bf16 v[126:129], v[136:139], v[190:193], v[126:129]
	v_mfma_f32_16x16x32_bf16 v[122:125], v[148:151], v[190:193], v[122:125]
	v_mfma_f32_16x16x32_bf16 v[114:117], v[136:139], v[212:215], v[114:117]
	v_mfma_f32_16x16x32_bf16 v[110:113], v[148:151], v[212:215], v[110:113]
	v_mfma_f32_16x16x32_bf16 v[98:101], v[136:139], v[224:227], v[98:101]
	v_mfma_f32_16x16x32_bf16 v[94:97], v[148:151], v[224:227], v[94:97]
	v_mfma_f32_16x16x32_bf16 v[82:85], v[136:139], v[232:235], v[82:85]
	v_mfma_f32_16x16x32_bf16 v[78:81], v[148:151], v[232:235], v[78:81]
	v_mfma_f32_16x16x32_bf16 v[126:129], v[144:147], v[194:197], v[126:129]
	v_mfma_f32_16x16x32_bf16 v[122:125], v[152:155], v[194:197], v[122:125]
	v_mfma_f32_16x16x32_bf16 v[114:117], v[144:147], v[220:223], v[114:117]
	v_mfma_f32_16x16x32_bf16 v[110:113], v[152:155], v[220:223], v[110:113]
	v_mfma_f32_16x16x32_bf16 v[98:101], v[144:147], v[228:231], v[98:101]
	v_mfma_f32_16x16x32_bf16 v[94:97], v[152:155], v[228:231], v[94:97]
	v_mfma_f32_16x16x32_bf16 v[82:85], v[144:147], v[236:239], v[82:85]
	v_mfma_f32_16x16x32_bf16 v[78:81], v[152:155], v[236:239], v[78:81]
	v_mfma_f32_16x16x32_bf16 v[118:121], v[156:159], v[190:193], v[118:121]
	v_mfma_f32_16x16x32_bf16 v[106:109], v[164:167], v[190:193], v[106:109]
	v_mfma_f32_16x16x32_bf16 v[102:105], v[156:159], v[212:215], v[102:105]
	v_mfma_f32_16x16x32_bf16 v[90:93], v[164:167], v[212:215], v[90:93]
	v_mfma_f32_16x16x32_bf16 v[86:89], v[156:159], v[224:227], v[86:89]
	v_mfma_f32_16x16x32_bf16 v[74:77], v[164:167], v[224:227], v[74:77]
	v_mfma_f32_16x16x32_bf16 v[70:73], v[156:159], v[232:235], v[70:73]
	v_mfma_f32_16x16x32_bf16 v[66:69], v[164:167], v[232:235], v[66:69]
	v_mfma_f32_16x16x32_bf16 v[118:121], v[160:163], v[194:197], v[118:121]
	v_mfma_f32_16x16x32_bf16 v[106:109], v[186:189], v[194:197], v[106:109]
	v_mfma_f32_16x16x32_bf16 v[102:105], v[160:163], v[220:223], v[102:105]
	v_mfma_f32_16x16x32_bf16 v[90:93], v[186:189], v[220:223], v[90:93]
	v_mfma_f32_16x16x32_bf16 v[86:89], v[160:163], v[228:231], v[86:89]
	v_mfma_f32_16x16x32_bf16 v[74:77], v[186:189], v[228:231], v[74:77]
	v_mfma_f32_16x16x32_bf16 v[70:73], v[160:163], v[236:239], v[70:73]
	v_mfma_f32_16x16x32_bf16 v[66:69], v[186:189], v[236:239], v[66:69]
	s_setprio 0
	s_barrier
; #define PG8_STAGE(bufoff, gbase, voff) do { _Pragma("unroll") for (int _i = 0; _i < 2; ++_i) \
;         __builtin_amdgcn_global_load_lds((const unsigned*)((const char*)(gbase) + (voff)[_i]), (PG8_LAS unsigned*)(lds + (bufoff) + ldsw + _i * 8192), 16, 0, 0); } while (0)
; #define PG8_LDA(dst, b, h) do { _Pragma("unroll") for (int m = 0; m < 4; ++m) _Pragma("unroll") for (int k = 0; k < 2; ++k) dst[m][k] = *(const PG8_LAS bf16x8*)(lds + PG8_SA(b, h) + aoff + m * 2048 + k * 1024); } while (0)
; #define PG8_LDB(dst, b, h) do { _Pragma("unroll") for (int n = 0; n < 2; ++n) _Pragma("unroll") for (int k = 0; k < 2; ++k) dst[n][k] = *(const PG8_LAS bf16x8*)(lds + PG8_SB(b, h) + boff + n * 2048 + k * 1024); } while (0)
; #define PG8_MMA(ai, bj, At, Bt) do { __builtin_amdgcn_s_setprio(1); _Pragma("unroll") for (int m = 0; m < 4; ++m) _Pragma("unroll") for (int n = 0; n < 2; ++n) _Pragma("unroll") for (int k = 0; k < 2; ++k) \
;         acc[ai][bj][m][n] = __builtin_amdgcn_mfma_f32_16x16x32_bf16(Bt[n][k], At[m][k], acc[ai][bj][m][n], 0, 0, 0); __builtin_amdgcn_s_setprio(0); } while (0)
; template <class Epi, class Sched, bool ALIGN_EPI = false, bool SP2 = false>
; __device__ __forceinline__ void gemm_phase(PG8_LAS unsigned char* lds, const Gemm g, const Sched& S, const Epi& E, int tid_in) {
;     ...
;             if constexpr (SP2) {
;             PG8_LDB(B0, 0, 0); PG8_LDB(B1, 0, 1); PG8_SCHED; PG8_LDA(At, 0, 0); PG8_STAGE(PG8_SA(1, 1), a1 + hstep, voffA);
;             PG8_WAIT_V(8); PG8_WAIT_L(0); PG8_BAR; PG8_MMA(0, 0, At, B0); PG8_MMA(0, 1, At, B1); PG8_BAR; PG8_SCHED;
;             PG8_LDA(At, 0, 1); PG8_STAGE(PG8_SB(0, 0), b2, voffB); PG8_STAGE(PG8_SB(0, 1), b2 + hstep, voffB); PG8_STAGE(PG8_SA(0, 0), a2, voffA);
;             PG8_WAIT_V(8); PG8_WAIT_L(0); PG8_BAR; PG8_MMA(1, 0, At, B0); PG8_MMA(1, 1, At, B1); PG8_BAR; PG8_SCHED;
;             PG8_LDB(B0, 1, 0); PG8_LDB(B1, 1, 1); PG8_SCHED; PG8_LDA(At, 1, 0); PG8_STAGE(PG8_SA(0, 1), a2 + hstep, voffA);
;             PG8_WAIT_V(8); PG8_WAIT_L(0); PG8_BAR; PG8_MMA(0, 0, At, B0); PG8_MMA(0, 1, At, B1); PG8_BAR; PG8_SCHED;
;             PG8_LDA(At, 1, 1); PG8_STAGE(PG8_SB(1, 0), b3, voffB); PG8_STAGE(PG8_SB(1, 1), b3 + hstep, voffB); PG8_STAGE(PG8_SA(1, 0), a3, voffA);
;             PG8_WAIT_V(8); PG8_WAIT_L(0); PG8_BAR; PG8_MMA(1, 0, At, B0); PG8_MMA(1, 1, At, B1); PG8_BAR; PG8_SCHED;
	s_add_i32 s24, s58, s35
	v_lshl_add_u64 v[168:169], v[168:169], 0, s[74:75]
	s_mov_b32 m0, s24
	ds_read_b128 v[190:193], v143 offset:49152
	ds_read_b128 v[194:197], v143 offset:50176
	ds_read_b128 v[212:215], v143 offset:51200
	ds_read_b128 v[220:223], v143 offset:52224
	ds_read_b128 v[224:227], v143 offset:53248
	ds_read_b128 v[228:231], v143 offset:54272
	ds_read_b128 v[232:235], v143 offset:55296
	ds_read_b128 v[236:239], v143 offset:56320
	global_load_lds_dwordx4 v[168:169], off
	s_add_i32 m0, s24, 0x2000
	s_add_u32 s24, s28, 0x160080
	v_lshl_add_u64 v[168:169], v[216:217], 0, s[74:75]
	s_addc_u32 s25, s29, 0
	s_add_i32 s28, s59, s35
	global_load_lds_dwordx4 v[168:169], off
	v_lshl_add_u64 v[168:169], s[24:25], 0, v[32:33]
	s_mov_b32 m0, s28
	s_nop 0
	global_load_lds_dwordx4 v[168:169], off
	v_lshl_add_u64 v[168:169], s[24:25], 0, v[130:131]
	s_add_i32 m0, s28, 0x2000
	s_nop 0
	global_load_lds_dwordx4 v[168:169], off
	v_lshl_add_u64 v[168:169], v[240:241], 0, s[74:75]
	s_mov_b32 m0, s48
	s_nop 0
	global_load_lds_dwordx4 v[168:169], off
	v_lshl_add_u64 v[168:169], v[242:243], 0, s[74:75]
	s_mov_b32 m0, s49
	s_nop 0
	global_load_lds_dwordx4 v[168:169], off
	s_waitcnt vmcnt(8)
	s_waitcnt lgkmcnt(0)
	.p2align	3
	s_setprio 1
	s_barrier
	v_mfma_f32_16x16x32_bf16 v[62:65], v[136:139], v[190:193], v[62:65]
	v_mfma_f32_16x16x32_bf16 v[58:61], v[148:151], v[190:193], v[58:61]
	v_mfma_f32_16x16x32_bf16 v[50:53], v[136:139], v[212:215], v[50:53]
	v_mfma_f32_16x16x32_bf16 v[46:49], v[148:151], v[212:215], v[46:49]
	v_mfma_f32_16x16x32_bf16 v[34:37], v[136:139], v[224:227], v[34:37]
	v_mfma_f32_16x16x32_bf16 v[28:31], v[148:151], v[224:227], v[28:31]
	v_mfma_f32_16x16x32_bf16 v[16:19], v[136:139], v[232:235], v[16:19]
	v_mfma_f32_16x16x32_bf16 v[12:15], v[148:151], v[232:235], v[12:15]
	v_mfma_f32_16x16x32_bf16 v[62:65], v[144:147], v[194:197], v[62:65]
	v_mfma_f32_16x16x32_bf16 v[58:61], v[152:155], v[194:197], v[58:61]
	v_mfma_f32_16x16x32_bf16 v[50:53], v[144:147], v[220:223], v[50:53]
	v_mfma_f32_16x16x32_bf16 v[46:49], v[152:155], v[220:223], v[46:49]
	v_mfma_f32_16x16x32_bf16 v[34:37], v[144:147], v[228:231], v[34:37]
	v_mfma_f32_16x16x32_bf16 v[28:31], v[152:155], v[228:231], v[28:31]
	v_mfma_f32_16x16x32_bf16 v[16:19], v[144:147], v[236:239], v[16:19]
	v_mfma_f32_16x16x32_bf16 v[12:15], v[152:155], v[236:239], v[12:15]
	v_mfma_f32_16x16x32_bf16 v[54:57], v[156:159], v[190:193], v[54:57]
	v_mfma_f32_16x16x32_bf16 v[42:45], v[164:167], v[190:193], v[42:45]
	v_mfma_f32_16x16x32_bf16 v[38:41], v[156:159], v[212:215], v[38:41]
	v_mfma_f32_16x16x32_bf16 v[24:27], v[164:167], v[212:215], v[24:27]
	v_mfma_f32_16x16x32_bf16 v[20:23], v[156:159], v[224:227], v[20:23]
	v_mfma_f32_16x16x32_bf16 v[8:11], v[164:167], v[224:227], v[8:11]
	v_mfma_f32_16x16x32_bf16 v[4:7], v[156:159], v[232:235], v[4:7]
	v_mfma_f32_16x16x32_bf16 v[0:3], v[164:167], v[232:235], v[0:3]
	v_mfma_f32_16x16x32_bf16 v[54:57], v[160:163], v[194:197], v[54:57]
	v_mfma_f32_16x16x32_bf16 v[42:45], v[186:189], v[194:197], v[42:45]
	v_mfma_f32_16x16x32_bf16 v[38:41], v[160:163], v[220:223], v[38:41]
	v_mfma_f32_16x16x32_bf16 v[24:27], v[186:189], v[220:223], v[24:27]
	v_mfma_f32_16x16x32_bf16 v[20:23], v[160:163], v[228:231], v[20:23]
	v_mfma_f32_16x16x32_bf16 v[8:11], v[186:189], v[228:231], v[8:11]
	v_mfma_f32_16x16x32_bf16 v[4:7], v[160:163], v[236:239], v[4:7]
	v_mfma_f32_16x16x32_bf16 v[0:3], v[186:189], v[236:239], v[0:3]
	s_setprio 0
	s_barrier
	s_add_i32 s57, s57, 2
	s_add_u32 s45, s45, 0x100
	s_addc_u32 s47, s47, 0
	s_cmpk_gt_u32 s57, 0x55
	s_mov_b64 s[24:25], s[26:27]
	s_cbranch_scc0 .LBB0_625
	s_and_b64 vcc, exec, s[20:21]
	s_cbranch_vccz .LBB0_628
	s_barrier
